# batched the serialized per-row sum-of-squares loads in the QKV and FFN-up epilogues (one wait instead of 4-8 round trips); removed the grid barrier after the last phase
# speedup vs baseline: 1.0008x; 1.0008x over previous
;     static __device__ __forceinline__ void unpk4(const u32x2 w, float (&o)[4]) { o[0] = bf_lo(w.x); o[1] = bf_hi(w.x); o[2] = bf_lo(w.y); o[3] = bf_hi(w.y); }
;     template <int N> static __device__ __forceinline__ u32x2 dpp_prev(const u32x2 pv, const u32x2 cur) { u32x2 r; r.x = dpp_prev1<N>(pv.x, cur.x); r.y = dpp_prev1<N>(pv.y, cur.y); return r; }
;     __device__ __forceinline__ void operator()(const f32x4 (&acc)[2][2][4][2], const Unit& u, int wr, int wc, int fr, int fq) const {
;     ...
;             for (int m = 0; m < 4; ++m) rs8[ai][m] = rsqrtf(SS[u.rb + (u.half ? 0 : ai * HALF) + wr * 64 + fr + 16 * m] * (1.f / 1024.f) + 1e-6f);
;     ...
;         } else {
; #pragma unroll
;         for (int bj = 0; bj < 2; ++bj)
; #pragma unroll
;           for (int hv = 0; hv < 2; ++hv) {
;             const int col = u.pn * BM + bj * HALF + wc * 32 + 8 * fq + 4 * hv;
;             float w0[4], w1[4], w2[4], bb[4];
;             ld4f(cw + col, w0); ld4f(cw + 2816 + col, w1); ld4f(cw + 2 * 2816 + col, w2); ld4f(cb + col, bb);
;             {
;                 const int i = fr & 7;
;                 u32x2 gq[4];
; #pragma unroll
;                 for (int m = 0; m < 4; ++m) { const int row = row0 + m * 16; gq[m] = *(const u32x2*)(G + (size_t)row * 2816 + col); }
; #pragma unroll
;                 for (int mh = 0; mh < 4; mh += 2) {
;                 f32x4 c0[4], c1[4];
; #pragma unroll
;                 for (int m = mh; m < mh + 2; ++m) { const int row = row0 + m * 16; const float* cx = ctx + (size_t)((row - 32768) >> 3) * 2 * 2816 + col;
;                     c0[m] = *(const f32x4*)cx; c1[m] = *(const f32x4*)(cx + 2816); }
; #pragma unroll
;                 for (int m = mh; m < mh + 2; ++m) { const int row = row0 + m * 16; const u32x2 cur = gq[m];
;                     const u32x2 q1 = dpp_prev<1>(cur, cur), q2 = dpp_prev<2>(cur, cur);
;                     float g0[4], g1[4], g2[4]; unpk4(cur, g0); unpk4(q1, g1); unpk4(q2, g2);
; #pragma unroll
;                     for (int j = 0; j < 4; ++j) { const float x1 = c1[m][j], x0 = c0[m][j];
;                         if (i < 1) g1[j] = x1;
;                         if (i < 2) g2[j] = (i == 1) ? x1 : x0; }
;                     finish(g0, g1, g2, w0, w1, w2, bb, acc[0][bj][m][hv], rs8[0][m], H + (size_t)row * 2816 + col); }
.LBB0_1007:
	v_readlane_b32 s0, v240, 29
	v_mov_b32_e32 v1, v218
	v_mov_b32_e32 v132, v219
	s_add_i32 s2, s2, s0
	v_readlane_b32 s0, v240, 31
	v_add_u32_e32 v210, s2, v1
	v_ashrrev_i32_e32 v211, 31, v210
	v_lshl_add_u64 v[2:3], v[210:211], 2, s[12:13]
	global_load_dword v241, v[2:3], off offset:64
	global_load_dword v242, v[2:3], off offset:128
	global_load_dword v243, v[2:3], off offset:192
	global_load_dword v2, v[2:3], off
	s_waitcnt lgkmcnt(0)
	v_add_u32_e32 v194, 16, v210
	v_ashrrev_i32_e32 v195, 31, v194
	v_add_u32_e32 v192, 32, v210
	v_ashrrev_i32_e32 v193, 31, v192
	v_add_u32_e32 v190, 48, v210
	v_ashrrev_i32_e32 v191, 31, v190
	s_cmpk_lt_i32 s7, 0x80
	s_waitcnt vmcnt(0)
	v_fmamk_f32 v2, v2, 0x3a800000, v224
	v_cmp_gt_f32_e32 vcc, s5, v2
	v_mul_f32_e32 v3, 0x4b800000, v2
	s_nop 0
	v_cndmask_b32_e32 v2, v2, v3, vcc
	v_rsq_f32_e32 v2, v2
	s_nop 0
	v_mul_f32_e32 v3, 0x45800000, v2
	v_cndmask_b32_e32 v188, v2, v3, vcc
	v_lshl_add_u64 v[2:3], v[194:195], 2, s[12:13]
	v_mov_b32_e32 v2, v241
	s_waitcnt vmcnt(0)
	v_fmamk_f32 v2, v2, 0x3a800000, v224
	v_cmp_gt_f32_e32 vcc, s5, v2
	v_mul_f32_e32 v3, 0x4b800000, v2
	s_nop 0
	v_cndmask_b32_e32 v2, v2, v3, vcc
	v_rsq_f32_e32 v2, v2
	s_nop 0
	v_mul_f32_e32 v3, 0x45800000, v2
	v_cndmask_b32_e32 v186, v2, v3, vcc
	v_lshl_add_u64 v[2:3], v[192:193], 2, s[12:13]
	v_mov_b32_e32 v2, v242
	s_waitcnt vmcnt(0)
	v_fmamk_f32 v2, v2, 0x3a800000, v224
	v_cmp_gt_f32_e32 vcc, s5, v2
	v_mul_f32_e32 v3, 0x4b800000, v2
	s_nop 0
	v_cndmask_b32_e32 v2, v2, v3, vcc
	v_rsq_f32_e32 v2, v2
	s_nop 0
	v_mul_f32_e32 v3, 0x45800000, v2
	v_cndmask_b32_e32 v184, v2, v3, vcc
	v_lshl_add_u64 v[2:3], v[190:191], 2, s[12:13]
	v_mov_b32_e32 v2, v243
	s_nop 0
	s_nop 0
	s_nop 0
	s_nop 0
	s_nop 0
	s_nop 0
	s_nop 0
	s_nop 0
	s_nop 0
	s_nop 0
	s_nop 0
	s_nop 0
	s_nop 0
	s_waitcnt vmcnt(0)
	v_fmamk_f32 v2, v2, 0x3a800000, v224
	v_cmp_gt_f32_e32 vcc, s5, v2
	v_mul_f32_e32 v3, 0x4b800000, v2
	s_nop 0
	v_cndmask_b32_e32 v2, v2, v3, vcc
	v_rsq_f32_e32 v2, v2
	s_nop 0
	v_mul_f32_e32 v3, 0x45800000, v2
	v_cndmask_b32_e32 v2, v2, v3, vcc
	v_lshl_add_u32 v3, v132, 3, s0
	s_mov_b64 s[0:1], -1
	s_cbranch_scc1 .LBB0_1009
	v_lshl_add_u32 v150, s70, 8, v3
	v_ashrrev_i32_e32 v151, 31, v150
	v_readlane_b32 s68, v240, 12
	v_lshlrev_b64 v[160:161], 1, v[150:151]
	v_readlane_b32 s69, v240, 13
	v_add_u32_e32 v134, 0xffff8000, v210
	s_mov_b64 s[86:87], s[54:55]
	v_lshl_add_u64 v[162:163], s[68:69], 0, v[160:161]
	v_mad_i64_i32 v[132:133], s[0:1], v210, s91, v[162:163]
	global_load_dwordx2 v[154:155], v[132:133], off
	v_lshlrev_b64 v[132:133], 2, v[150:151]
	v_lshl_add_u64 v[156:157], s[82:83], 0, v[132:133]
	v_ashrrev_i32_e32 v151, 3, v134
	v_mad_i64_i32 v[134:135], s[0:1], v151, s45, v[156:157]
	v_readlane_b32 s52, v240, 62
	v_add_co_u32_e32 v136, vcc, s41, v134
	v_readlane_b32 s53, v240, 63
	s_nop 0
	v_addc_co_u32_e32 v137, vcc, 0, v135, vcc
	global_load_dwordx4 v[170:173], v[134:135], off
	global_load_dwordx4 v[174:177], v[136:137], off offset:3072
	v_readlane_b32 s54, v239, 0
	v_readlane_b32 s55, v239, 1
	v_readlane_b32 s66, v239, 12
	v_readlane_b32 s67, v239, 13
	v_readlane_b32 s52, v240, 19
	v_readlane_b32 s53, v240, 20
	v_lshl_add_u64 v[134:135], s[66:67], 0, v[132:133]
	v_readlane_b32 s54, v240, 21
	v_lshl_add_u64 v[136:137], s[88:89], 0, v[132:133]
	global_load_dwordx4 v[140:143], v[134:135], off
	global_load_dwordx4 v[144:147], v[136:137], off
	v_lshl_add_u64 v[134:135], s[52:53], 0, v[132:133]
	v_readlane_b32 s55, v240, 22
	global_load_dwordx4 v[136:139], v[134:135], off
	v_add_u32_e32 v152, 0xffff8010, v210
	v_lshl_add_u64 v[132:133], s[54:55], 0, v[132:133]
	global_load_dwordx4 v[132:135], v[132:133], off
	v_readlane_b32 s0, v240, 58
	v_readlane_b32 s1, v240, 59
	v_ashrrev_i32_e32 v168, 3, v152
	v_and_b32_e32 v169, 7, v1
	v_mov_b64_e32 v[158:159], s[0:1]
	v_mad_i64_i32 v[180:181], s[0:1], v168, s45, v[156:157]
	v_mad_i64_i32 v[164:165], s[0:1], v194, s91, v[162:163]
	v_mad_i64_i32 v[178:179], s[0:1], v192, s91, v[162:163]
	v_mad_i64_i32 v[162:163], s[0:1], v190, s91, v[162:163]
	v_add_co_u32_e32 v212, vcc, s41, v180
	global_load_dwordx2 v[166:167], v[164:165], off
	s_nop 0
	global_load_dwordx2 v[164:165], v[178:179], off
	s_nop 0
	global_load_dwordx2 v[162:163], v[162:163], off
	v_addc_co_u32_e32 v213, vcc, 0, v181, vcc
	global_load_dwordx4 v[178:181], v[180:181], off
	s_nop 0
	global_load_dwordx4 v[212:215], v[212:213], off offset:3072
	v_mad_i64_i32 v[152:153], s[0:1], v210, s91, v[158:159]
	v_cmp_eq_u32_e32 vcc, 1, v169
	v_cmp_eq_u32_e64 s[0:1], 0, v169
	v_cmp_gt_u32_e64 s[8:9], 2, v169
	v_mov_b64_e32 v[148:149], s[36:37]
	v_lshl_add_u64 v[182:183], v[152:153], 0, v[160:161]
	v_readlane_b32 s64, v239, 10
	v_readlane_b32 s65, v239, 11
	v_readlane_b32 s64, v240, 23
	v_readlane_b32 s65, v240, 24
	v_readlane_b32 s56, v239, 2
	v_readlane_b32 s57, v239, 3
	v_readlane_b32 s58, v239, 4
	v_readlane_b32 s59, v239, 5
	v_readlane_b32 s60, v239, 6
	v_readlane_b32 s61, v239, 7
	v_readlane_b32 s62, v239, 8
	v_readlane_b32 s63, v239, 9
	s_waitcnt vmcnt(11)
	v_mov_b32_dpp v185, v154 row_ror:1 row_mask:0xf bank_mask:0xf bound_ctrl:1
	v_mov_b32_dpp v187, v155 row_ror:1 row_mask:0xf bank_mask:0xf bound_ctrl:1
	v_mov_b32_dpp v189, v154 row_ror:2 row_mask:0xf bank_mask:0xf bound_ctrl:1
	v_mov_b32_dpp v185, v154 row_shr:1 row_mask:0xf bank_mask:0xf
	v_mov_b32_dpp v187, v155 row_shr:1 row_mask:0xf bank_mask:0xf
	v_mov_b32_dpp v189, v154 row_shr:2 row_mask:0xf bank_mask:0xf
	v_mov_b32_dpp v191, v155 row_ror:2 row_mask:0xf bank_mask:0xf bound_ctrl:1
	v_lshlrev_b32_e32 v226, 16, v154
	v_and_b32_e32 v227, 0xffff0000, v154
	v_mov_b32_dpp v191, v155 row_shr:2 row_mask:0xf bank_mask:0xf
	s_waitcnt vmcnt(9)
; __device__ __forceinline__ unsigned cvt_pk_bf16(float lo, float hi) { unsigned r; asm volatile("v_cvt_pk_bf16_f32 %0, %1, %2" : "=v"(r) : "v"(lo), "v"(hi)); return r; }
;     static __device__ __forceinline__ void unpk4(const u32x2 w, float (&o)[4]) { o[0] = bf_lo(w.x); o[1] = bf_hi(w.x); o[2] = bf_lo(w.y); o[3] = bf_hi(w.y); }
;     template <int N> static __device__ __forceinline__ u32x2 dpp_prev(const u32x2 pv, const u32x2 cur) { u32x2 r; r.x = dpp_prev1<N>(pv.x, cur.x); r.y = dpp_prev1<N>(pv.y, cur.y); return r; }
;     static __device__ __forceinline__ void finish(const float (&g0)[4], const float (&g1)[4], const float (&g2)[4], const float (&w0)[4], const float (&w1)[4], const float (&w2)[4], const float (&bb)[4],
;                                                   const f32x4 v, float rs, bf16_t* dst) {
;         float h[4];
; #pragma unroll
;         for (int j = 0; j < 4; j += 2) {
;             const f32x2 gc = (f32x2){bb[j] + w0[j] * g2[j] + w1[j] * g1[j] + w2[j] * g0[j], bb[j + 1] + w0[j + 1] * g2[j + 1] + w1[j + 1] * g1[j + 1] + w2[j + 1] * g0[j + 1]};
;             const f32x2 ge = gelu_pk(gc); h[j] = ge.x * v[j] * rs; h[j + 1] = ge.y * v[j + 1] * rs; }
;         u32x2 w; w.x = cvt_pk_bf16(h[0], h[1]); w.y = cvt_pk_bf16(h[2], h[3]);
;         *(u32x2*)dst = w;
;     }
;     __device__ __forceinline__ void operator()(const f32x4 (&acc)[2][2][4][2], const Unit& u, int wr, int wc, int fr, int fq) const {
;     ...
;                 for (int m = mh; m < mh + 2; ++m) { const int row = row0 + m * 16; const u32x2 cur = gq[m];
;                     const u32x2 q1 = dpp_prev<1>(cur, cur), q2 = dpp_prev<2>(cur, cur);
;                     float g0[4], g1[4], g2[4]; unpk4(cur, g0); unpk4(q1, g1); unpk4(q2, g2);
; #pragma unroll
;                     for (int j = 0; j < 4; ++j) { const float x1 = c1[m][j], x0 = c0[m][j];
;                         if (i < 1) g1[j] = x1;
;                         if (i < 2) g2[j] = (i == 1) ? x1 : x0; }
;                     finish(g0, g1, g2, w0, w1, w2, bb, acc[0][bj][m][hv], rs8[0][m], H + (size_t)row * 2816 + col); }
	v_cndmask_b32_e32 v154, v170, v174, vcc
	v_cndmask_b32_e32 v193, v171, v175, vcc
	v_cndmask_b32_e32 v195, v172, v176, vcc
	v_cndmask_b32_e32 v211, v173, v177, vcc
	v_lshlrev_b32_e32 v170, 16, v185
	v_and_b32_e32 v171, 0xffff0000, v185
	v_lshlrev_b32_e32 v172, 16, v187
	v_and_b32_e32 v173, 0xffff0000, v187
	v_lshlrev_b32_e32 v185, 16, v189
	v_and_b32_e32 v187, 0xffff0000, v189
	v_cndmask_b32_e64 v173, v173, v177, s[0:1]
	v_cndmask_b32_e64 v172, v172, v176, s[0:1]
	v_cndmask_b32_e64 v177, v187, v193, s[8:9]
	v_cndmask_b32_e64 v176, v185, v154, s[8:9]
	v_lshlrev_b32_e32 v189, 16, v191
	v_and_b32_e32 v191, 0xffff0000, v191
	v_cndmask_b32_e64 v171, v171, v175, s[0:1]
	v_cndmask_b32_e64 v170, v170, v174, s[0:1]
	s_waitcnt vmcnt(7)
	v_pk_fma_f32 v[176:177], v[140:141], v[176:177], v[144:145]
	v_cndmask_b32_e64 v175, v191, v211, s[8:9]
	v_cndmask_b32_e64 v174, v189, v195, s[8:9]
	s_waitcnt vmcnt(6)
	v_pk_fma_f32 v[170:171], v[136:137], v[170:171], v[176:177]
	v_pk_fma_f32 v[174:175], v[142:143], v[174:175], v[146:147]
	s_waitcnt vmcnt(5)
	v_pk_fma_f32 v[170:171], v[132:133], v[226:227], v[170:171]
	v_pk_fma_f32 v[172:173], v[138:139], v[172:173], v[174:175]
	v_pk_mul_f32 v[174:175], v[170:171], s[30:31] op_sel_hi:[1,0]
	v_pk_mul_f32 v[170:171], v[170:171], 0.5 op_sel_hi:[1,0]
	v_med3_f32 v174, v174, s47, v225
	v_med3_f32 v175, v175, s47, v225
	v_pk_mul_f32 v[176:177], v[174:175], v[174:175]
	s_nop 0
	v_pk_fma_f32 v[226:227], v[176:177], s[34:35], v[148:149] op_sel_hi:[1,0,0] neg_lo:[1,0,0] neg_hi:[1,0,0]
	s_nop 0
	v_pk_fma_f32 v[226:227], v[176:177], v[226:227], s[38:39] op_sel_hi:[1,1,0]
	s_nop 0
	v_pk_fma_f32 v[226:227], v[176:177], v[226:227], s[40:41] op_sel_hi:[1,1,0]
	s_nop 0
	v_pk_fma_f32 v[226:227], v[176:177], v[226:227], s[42:43] op_sel_hi:[1,1,0]
	s_nop 0
	v_pk_fma_f32 v[226:227], v[176:177], v[226:227], s[44:45] op_sel_hi:[1,1,0]
	s_nop 0
	v_pk_fma_f32 v[226:227], v[176:177], v[226:227], s[46:47] op_sel_hi:[1,1,0]
	s_nop 0
	v_pk_fma_f32 v[176:177], v[176:177], v[226:227], s[48:49] op_sel_hi:[1,1,0]
	s_nop 0
	v_pk_mul_f32 v[174:175], v[174:175], v[176:177]
	s_nop 0
	v_pk_fma_f32 v[170:171], v[170:171], v[174:175], v[170:171]
	s_nop 0
	v_mul_f32_e32 v154, v128, v170
	v_mul_f32_e32 v169, v188, v154
	v_mul_f32_e32 v154, v129, v171
	v_mul_f32_e32 v176, v188, v154
	v_lshlrev_b32_e32 v154, 16, v155
	v_and_b32_e32 v155, 0xffff0000, v155
	v_pk_fma_f32 v[154:155], v[134:135], v[154:155], v[172:173]
	s_nop 0
	v_pk_mul_f32 v[170:171], v[154:155], s[30:31] op_sel_hi:[1,0]
	v_pk_mul_f32 v[154:155], v[154:155], 0.5 op_sel_hi:[1,0]
	v_med3_f32 v170, v170, s47, v225
	v_med3_f32 v171, v171, s47, v225
	v_pk_mul_f32 v[172:173], v[170:171], v[170:171]
	s_nop 0
	v_pk_fma_f32 v[174:175], v[172:173], s[34:35], v[148:149] op_sel_hi:[1,0,0] neg_lo:[1,0,0] neg_hi:[1,0,0]
	s_nop 0
	v_pk_fma_f32 v[174:175], v[172:173], v[174:175], s[38:39] op_sel_hi:[1,1,0]
	s_nop 0
	v_pk_fma_f32 v[174:175], v[172:173], v[174:175], s[40:41] op_sel_hi:[1,1,0]
	s_nop 0
	v_pk_fma_f32 v[174:175], v[172:173], v[174:175], s[42:43] op_sel_hi:[1,1,0]
	s_nop 0
	v_pk_fma_f32 v[174:175], v[172:173], v[174:175], s[44:45] op_sel_hi:[1,1,0]
	s_nop 0
	v_pk_fma_f32 v[174:175], v[172:173], v[174:175], s[46:47] op_sel_hi:[1,1,0]
	s_nop 0
	v_pk_fma_f32 v[172:173], v[172:173], v[174:175], s[48:49] op_sel_hi:[1,1,0]
	s_nop 0
	v_pk_mul_f32 v[170:171], v[170:171], v[172:173]
	s_nop 0
	v_pk_fma_f32 v[154:155], v[154:155], v[170:171], v[154:155]
	s_nop 0
	v_mul_f32_e32 v154, v130, v154
	v_mul_f32_e32 v170, v188, v154
	v_mul_f32_e32 v154, v131, v155
	v_mul_f32_e32 v155, v188, v154
	v_cvt_pk_bf16_f32 v154, v169, v176
	v_cvt_pk_bf16_f32 v155, v170, v155
	global_store_dwordx2 v[182:183], v[154:155], off
	s_waitcnt vmcnt(5)
	v_mov_b32_dpp v169, v166 row_ror:2 row_mask:0xf bank_mask:0xf bound_ctrl:1
	v_mov_b32_dpp v154, v166 row_ror:1 row_mask:0xf bank_mask:0xf bound_ctrl:1
	v_mov_b32_dpp v155, v167 row_ror:1 row_mask:0xf bank_mask:0xf bound_ctrl:1
	v_mov_b32_dpp v170, v167 row_ror:2 row_mask:0xf bank_mask:0xf bound_ctrl:1
	v_mov_b32_dpp v154, v166 row_shr:1 row_mask:0xf bank_mask:0xf
	v_mov_b32_dpp v155, v167 row_shr:1 row_mask:0xf bank_mask:0xf
	v_mov_b32_dpp v169, v166 row_shr:2 row_mask:0xf bank_mask:0xf
	v_mov_b32_dpp v170, v167 row_shr:2 row_mask:0xf bank_mask:0xf
	v_lshlrev_b32_e32 v172, 16, v154
	v_and_b32_e32 v154, 0xffff0000, v154
	v_lshlrev_b32_e32 v174, 16, v155
	v_and_b32_e32 v155, 0xffff0000, v155
	v_lshlrev_b32_e32 v176, 16, v169
	v_and_b32_e32 v169, 0xffff0000, v169
	v_lshlrev_b32_e32 v177, 16, v170
	v_and_b32_e32 v175, 0xffff0000, v170
	s_waitcnt vmcnt(1)
; __device__ __forceinline__ unsigned cvt_pk_bf16(float lo, float hi) { unsigned r; asm volatile("v_cvt_pk_bf16_f32 %0, %1, %2" : "=v"(r) : "v"(lo), "v"(hi)); return r; }
;     static __device__ __forceinline__ void unpk4(const u32x2 w, float (&o)[4]) { o[0] = bf_lo(w.x); o[1] = bf_hi(w.x); o[2] = bf_lo(w.y); o[3] = bf_hi(w.y); }
;     template <int N> static __device__ __forceinline__ u32x2 dpp_prev(const u32x2 pv, const u32x2 cur) { u32x2 r; r.x = dpp_prev1<N>(pv.x, cur.x); r.y = dpp_prev1<N>(pv.y, cur.y); return r; }
;     static __device__ __forceinline__ void finish(const float (&g0)[4], const float (&g1)[4], const float (&g2)[4], const float (&w0)[4], const float (&w1)[4], const float (&w2)[4], const float (&bb)[4],
;                                                   const f32x4 v, float rs, bf16_t* dst) {
;         float h[4];
; #pragma unroll
;         for (int j = 0; j < 4; j += 2) {
;             const f32x2 gc = (f32x2){bb[j] + w0[j] * g2[j] + w1[j] * g1[j] + w2[j] * g0[j], bb[j + 1] + w0[j + 1] * g2[j + 1] + w1[j + 1] * g1[j + 1] + w2[j + 1] * g0[j + 1]};
;             const f32x2 ge = gelu_pk(gc); h[j] = ge.x * v[j] * rs; h[j + 1] = ge.y * v[j + 1] * rs; }
;         u32x2 w; w.x = cvt_pk_bf16(h[0], h[1]); w.y = cvt_pk_bf16(h[2], h[3]);
;         *(u32x2*)dst = w;
;     }
;     __device__ __forceinline__ void operator()(const f32x4 (&acc)[2][2][4][2], const Unit& u, int wr, int wc, int fr, int fq) const {
;     ...
;                 for (int m = mh; m < mh + 2; ++m) { const int row = row0 + m * 16; const float* cx = ctx + (size_t)((row - 32768) >> 3) * 2 * 2816 + col;
;                     c0[m] = *(const f32x4*)cx; c1[m] = *(const f32x4*)(cx + 2816); }
; #pragma unroll
;                 for (int m = mh; m < mh + 2; ++m) { const int row = row0 + m * 16; const u32x2 cur = gq[m];
;                     const u32x2 q1 = dpp_prev<1>(cur, cur), q2 = dpp_prev<2>(cur, cur);
;                     float g0[4], g1[4], g2[4]; unpk4(cur, g0); unpk4(q1, g1); unpk4(q2, g2);
; #pragma unroll
;                     for (int j = 0; j < 4; ++j) { const float x1 = c1[m][j], x0 = c0[m][j];
;                         if (i < 1) g1[j] = x1;
;                         if (i < 2) g2[j] = (i == 1) ? x1 : x0; }
;                     finish(g0, g1, g2, w0, w1, w2, bb, acc[0][bj][m][hv], rs8[0][m], H + (size_t)row * 2816 + col); }
	v_cndmask_b32_e64 v171, v154, v213, s[0:1]
	v_cndmask_b32_e64 v170, v172, v212, s[0:1]
	v_cndmask_b32_e64 v173, v155, v215, s[0:1]
	v_cndmask_b32_e64 v172, v174, v214, s[0:1]
	v_cndmask_b32_e32 v154, v178, v212, vcc
	v_cndmask_b32_e32 v155, v179, v213, vcc
	v_cndmask_b32_e32 v174, v180, v214, vcc
	v_cndmask_b32_e64 v174, v177, v174, s[8:9]
	v_cndmask_b32_e64 v177, v169, v155, s[8:9]
	v_cndmask_b32_e64 v176, v176, v154, s[8:9]
	v_cndmask_b32_e32 v178, v181, v215, vcc
	v_pk_fma_f32 v[176:177], v[140:141], v[176:177], v[144:145]
	v_cndmask_b32_e64 v175, v175, v178, s[8:9]
	v_lshlrev_b32_e32 v180, 16, v166
	v_and_b32_e32 v181, 0xffff0000, v166
	v_pk_fma_f32 v[170:171], v[136:137], v[170:171], v[176:177]
	v_pk_fma_f32 v[174:175], v[142:143], v[174:175], v[146:147]
	v_pk_fma_f32 v[170:171], v[132:133], v[180:181], v[170:171]
	v_pk_fma_f32 v[172:173], v[138:139], v[172:173], v[174:175]
	v_pk_mul_f32 v[174:175], v[170:171], s[30:31] op_sel_hi:[1,0]
	v_pk_mul_f32 v[170:171], v[170:171], 0.5 op_sel_hi:[1,0]
	v_med3_f32 v174, v174, s47, v225
	v_med3_f32 v175, v175, s47, v225
	v_pk_mul_f32 v[176:177], v[174:175], v[174:175]
	v_mad_i64_i32 v[154:155], s[10:11], v194, s91, v[158:159]
	v_pk_fma_f32 v[180:181], v[176:177], s[34:35], v[148:149] op_sel_hi:[1,0,0] neg_lo:[1,0,0] neg_hi:[1,0,0]
	v_lshl_add_u64 v[178:179], v[154:155], 0, v[160:161]
	v_pk_fma_f32 v[180:181], v[176:177], v[180:181], s[38:39] op_sel_hi:[1,1,0]
	s_nop 0
	v_pk_fma_f32 v[180:181], v[176:177], v[180:181], s[40:41] op_sel_hi:[1,1,0]
	s_nop 0
	v_pk_fma_f32 v[180:181], v[176:177], v[180:181], s[42:43] op_sel_hi:[1,1,0]
	s_nop 0
	v_pk_fma_f32 v[180:181], v[176:177], v[180:181], s[44:45] op_sel_hi:[1,1,0]
	s_nop 0
	v_pk_fma_f32 v[180:181], v[176:177], v[180:181], s[46:47] op_sel_hi:[1,1,0]
	s_nop 0
	v_pk_fma_f32 v[176:177], v[176:177], v[180:181], s[48:49] op_sel_hi:[1,1,0]
	s_nop 0
	v_pk_mul_f32 v[174:175], v[174:175], v[176:177]
	s_nop 0
	v_pk_fma_f32 v[170:171], v[170:171], v[174:175], v[170:171]
	s_nop 0
	v_mul_f32_e32 v166, v120, v170
	v_mul_f32_e32 v169, v186, v166
	v_mul_f32_e32 v166, v121, v171
	v_mul_f32_e32 v176, v186, v166
	v_lshlrev_b32_e32 v166, 16, v167
	v_and_b32_e32 v167, 0xffff0000, v167
	v_pk_fma_f32 v[166:167], v[134:135], v[166:167], v[172:173]
	s_nop 0
	v_pk_mul_f32 v[170:171], v[166:167], s[30:31] op_sel_hi:[1,0]
	v_pk_mul_f32 v[166:167], v[166:167], 0.5 op_sel_hi:[1,0]
	v_med3_f32 v170, v170, s47, v225
	v_med3_f32 v171, v171, s47, v225
	v_pk_mul_f32 v[172:173], v[170:171], v[170:171]
	s_nop 0
	v_pk_fma_f32 v[174:175], v[172:173], s[34:35], v[148:149] op_sel_hi:[1,0,0] neg_lo:[1,0,0] neg_hi:[1,0,0]
	s_nop 0
	v_pk_fma_f32 v[174:175], v[172:173], v[174:175], s[38:39] op_sel_hi:[1,1,0]
	s_nop 0
	v_pk_fma_f32 v[174:175], v[172:173], v[174:175], s[40:41] op_sel_hi:[1,1,0]
	s_nop 0
	v_pk_fma_f32 v[174:175], v[172:173], v[174:175], s[42:43] op_sel_hi:[1,1,0]
	s_nop 0
	v_pk_fma_f32 v[174:175], v[172:173], v[174:175], s[44:45] op_sel_hi:[1,1,0]
	s_nop 0
	v_pk_fma_f32 v[174:175], v[172:173], v[174:175], s[46:47] op_sel_hi:[1,1,0]
	s_nop 0
	v_pk_fma_f32 v[172:173], v[172:173], v[174:175], s[48:49] op_sel_hi:[1,1,0]
	s_nop 0
	v_pk_mul_f32 v[170:171], v[170:171], v[172:173]
	s_nop 0
	v_pk_fma_f32 v[166:167], v[166:167], v[170:171], v[166:167]
	s_nop 0
	v_mul_f32_e32 v166, v122, v166
	v_mul_f32_e32 v170, v186, v166
	v_mul_f32_e32 v166, v123, v167
	v_mul_f32_e32 v167, v186, v166
	v_cvt_pk_bf16_f32 v166, v169, v176
	v_cvt_pk_bf16_f32 v167, v170, v167
	global_store_dwordx2 v[178:179], v[166:167], off
	v_add_u32_e32 v166, 0xffff8020, v210
	v_ashrrev_i32_e32 v166, 3, v166
	v_mad_i64_i32 v[174:175], s[10:11], v166, s45, v[156:157]
	v_add_co_u32_e64 v170, s[10:11], s41, v174
	v_add_u32_e32 v167, 0xffff8030, v210
	s_nop 0
	v_addc_co_u32_e64 v171, s[10:11], 0, v175, s[10:11]
	global_load_dwordx4 v[170:173], v[170:171], off offset:3072
	s_nop 0
	global_load_dwordx4 v[174:177], v[174:175], off
	v_ashrrev_i32_e32 v167, 3, v167
	v_mad_i64_i32 v[156:157], s[10:11], v167, s45, v[156:157]
	v_add_co_u32_e64 v182, s[10:11], s41, v156
	v_mov_b32_dpp v169, v164 row_ror:2 row_mask:0xf bank_mask:0xf bound_ctrl:1
	s_nop 0
	v_addc_co_u32_e64 v183, s[10:11], 0, v157, s[10:11]
	global_load_dwordx4 v[178:181], v[156:157], off
	global_load_dwordx4 v[212:215], v[182:183], off offset:3072
	v_mov_b32_dpp v156, v164 row_ror:1 row_mask:0xf bank_mask:0xf bound_ctrl:1
	v_mov_b32_dpp v157, v165 row_ror:1 row_mask:0xf bank_mask:0xf bound_ctrl:1
	v_mov_b32_dpp v169, v164 row_shr:2 row_mask:0xf bank_mask:0xf
	v_mov_b32_dpp v156, v164 row_shr:1 row_mask:0xf bank_mask:0xf
	v_mov_b32_dpp v157, v165 row_shr:1 row_mask:0xf bank_mask:0xf
	v_mov_b32_dpp v182, v165 row_ror:2 row_mask:0xf bank_mask:0xf bound_ctrl:1
	v_lshlrev_b32_e32 v185, 16, v156
	v_and_b32_e32 v156, 0xffff0000, v156
	v_lshlrev_b32_e32 v187, 16, v157
	v_and_b32_e32 v157, 0xffff0000, v157
	v_mov_b32_dpp v182, v165 row_shr:2 row_mask:0xf bank_mask:0xf
	v_lshlrev_b32_e32 v189, 16, v169
	v_and_b32_e32 v169, 0xffff0000, v169
	v_lshlrev_b32_e32 v191, 16, v182
	v_and_b32_e32 v193, 0xffff0000, v182
	s_waitcnt vmcnt(3)
	v_cndmask_b32_e64 v183, v156, v171, s[0:1]
	v_cndmask_b32_e64 v227, v157, v173, s[0:1]
	s_waitcnt vmcnt(2)
; __device__ __forceinline__ unsigned cvt_pk_bf16(float lo, float hi) { unsigned r; asm volatile("v_cvt_pk_bf16_f32 %0, %1, %2" : "=v"(r) : "v"(lo), "v"(hi)); return r; }
;     static __device__ __forceinline__ void unpk4(const u32x2 w, float (&o)[4]) { o[0] = bf_lo(w.x); o[1] = bf_hi(w.x); o[2] = bf_lo(w.y); o[3] = bf_hi(w.y); }
;     template <int N> static __device__ __forceinline__ u32x2 dpp_prev(const u32x2 pv, const u32x2 cur) { u32x2 r; r.x = dpp_prev1<N>(pv.x, cur.x); r.y = dpp_prev1<N>(pv.y, cur.y); return r; }
;     static __device__ __forceinline__ void finish(const float (&g0)[4], const float (&g1)[4], const float (&g2)[4], const float (&w0)[4], const float (&w1)[4], const float (&w2)[4], const float (&bb)[4],
;                                                   const f32x4 v, float rs, bf16_t* dst) {
;         float h[4];
; #pragma unroll
;         for (int j = 0; j < 4; j += 2) {
;             const f32x2 gc = (f32x2){bb[j] + w0[j] * g2[j] + w1[j] * g1[j] + w2[j] * g0[j], bb[j + 1] + w0[j + 1] * g2[j + 1] + w1[j + 1] * g1[j + 1] + w2[j + 1] * g0[j + 1]};
;             const f32x2 ge = gelu_pk(gc); h[j] = ge.x * v[j] * rs; h[j + 1] = ge.y * v[j + 1] * rs; }
;         u32x2 w; w.x = cvt_pk_bf16(h[0], h[1]); w.y = cvt_pk_bf16(h[2], h[3]);
;         *(u32x2*)dst = w;
;     }
;     __device__ __forceinline__ void operator()(const f32x4 (&acc)[2][2][4][2], const Unit& u, int wr, int wc, int fr, int fq) const {
;     ...
;                 for (int m = mh; m < mh + 2; ++m) { const int row = row0 + m * 16; const u32x2 cur = gq[m];
;                     const u32x2 q1 = dpp_prev<1>(cur, cur), q2 = dpp_prev<2>(cur, cur);
;                     float g0[4], g1[4], g2[4]; unpk4(cur, g0); unpk4(q1, g1); unpk4(q2, g2);
; #pragma unroll
;                     for (int j = 0; j < 4; ++j) { const float x1 = c1[m][j], x0 = c0[m][j];
;                         if (i < 1) g1[j] = x1;
;                         if (i < 2) g2[j] = (i == 1) ? x1 : x0; }
;                     finish(g0, g1, g2, w0, w1, w2, bb, acc[0][bj][m][hv], rs8[0][m], H + (size_t)row * 2816 + col); }
	v_cndmask_b32_e32 v156, v174, v170, vcc
	v_cndmask_b32_e32 v157, v175, v171, vcc
	v_cndmask_b32_e64 v182, v185, v170, s[0:1]
	v_cndmask_b32_e64 v226, v187, v172, s[0:1]
	v_cndmask_b32_e32 v170, v176, v172, vcc
	v_cndmask_b32_e32 v171, v177, v173, vcc
	v_cndmask_b32_e64 v173, v169, v157, s[8:9]
	v_cndmask_b32_e64 v172, v189, v156, s[8:9]
	v_pk_fma_f32 v[172:173], v[140:141], v[172:173], v[144:145]
	v_lshlrev_b32_e32 v176, 16, v164
	v_and_b32_e32 v177, 0xffff0000, v164
	v_pk_fma_f32 v[172:173], v[136:137], v[182:183], v[172:173]
	v_cndmask_b32_e64 v171, v193, v171, s[8:9]
	v_pk_fma_f32 v[172:173], v[132:133], v[176:177], v[172:173]
	v_cndmask_b32_e64 v170, v191, v170, s[8:9]
	v_pk_mul_f32 v[176:177], v[172:173], s[30:31] op_sel_hi:[1,0]
	v_pk_fma_f32 v[170:171], v[142:143], v[170:171], v[146:147]
	v_med3_f32 v176, v176, s47, v225
	v_med3_f32 v177, v177, s47, v225
	v_pk_mul_f32 v[182:183], v[176:177], v[176:177]
	v_pk_fma_f32 v[170:171], v[138:139], v[226:227], v[170:171]
	v_pk_fma_f32 v[226:227], v[182:183], s[34:35], v[148:149] op_sel_hi:[1,0,0] neg_lo:[1,0,0] neg_hi:[1,0,0]
	v_pk_mul_f32 v[172:173], v[172:173], 0.5 op_sel_hi:[1,0]
	v_pk_fma_f32 v[226:227], v[182:183], v[226:227], s[38:39] op_sel_hi:[1,1,0]
	v_mad_i64_i32 v[156:157], s[10:11], v192, s91, v[158:159]
	v_pk_fma_f32 v[226:227], v[182:183], v[226:227], s[40:41] op_sel_hi:[1,1,0]
	v_lshl_add_u64 v[174:175], v[156:157], 0, v[160:161]
	v_pk_fma_f32 v[226:227], v[182:183], v[226:227], s[42:43] op_sel_hi:[1,1,0]
	v_mad_i64_i32 v[158:159], s[10:11], v190, s91, v[158:159]
	v_pk_fma_f32 v[226:227], v[182:183], v[226:227], s[44:45] op_sel_hi:[1,1,0]
	v_lshl_add_u64 v[160:161], v[158:159], 0, v[160:161]
	v_pk_fma_f32 v[226:227], v[182:183], v[226:227], s[46:47] op_sel_hi:[1,1,0]
	s_nop 0
	v_pk_fma_f32 v[182:183], v[182:183], v[226:227], s[48:49] op_sel_hi:[1,1,0]
	s_nop 0
	v_pk_mul_f32 v[176:177], v[176:177], v[182:183]
	s_nop 0
	v_pk_fma_f32 v[172:173], v[172:173], v[176:177], v[172:173]
	s_nop 0
	v_mul_f32_e32 v164, v112, v172
	v_mul_f32_e32 v169, v184, v164
	v_mul_f32_e32 v164, v113, v173
	v_mul_f32_e32 v182, v184, v164
	v_lshlrev_b32_e32 v164, 16, v165
	v_and_b32_e32 v165, 0xffff0000, v165
	v_pk_fma_f32 v[164:165], v[134:135], v[164:165], v[170:171]
	s_nop 0
	v_pk_mul_f32 v[170:171], v[164:165], s[30:31] op_sel_hi:[1,0]
	v_pk_mul_f32 v[164:165], v[164:165], 0.5 op_sel_hi:[1,0]
	v_med3_f32 v170, v170, s47, v225
	v_med3_f32 v171, v171, s47, v225
	v_pk_mul_f32 v[172:173], v[170:171], v[170:171]
	s_nop 0
	v_pk_fma_f32 v[176:177], v[172:173], s[34:35], v[148:149] op_sel_hi:[1,0,0] neg_lo:[1,0,0] neg_hi:[1,0,0]
	s_nop 0
	v_pk_fma_f32 v[176:177], v[172:173], v[176:177], s[38:39] op_sel_hi:[1,1,0]
	s_nop 0
	v_pk_fma_f32 v[176:177], v[172:173], v[176:177], s[40:41] op_sel_hi:[1,1,0]
	s_nop 0
	v_pk_fma_f32 v[176:177], v[172:173], v[176:177], s[42:43] op_sel_hi:[1,1,0]
	s_nop 0
	v_pk_fma_f32 v[176:177], v[172:173], v[176:177], s[44:45] op_sel_hi:[1,1,0]
	s_nop 0
	v_pk_fma_f32 v[176:177], v[172:173], v[176:177], s[46:47] op_sel_hi:[1,1,0]
	s_nop 0
	v_pk_fma_f32 v[172:173], v[172:173], v[176:177], s[48:49] op_sel_hi:[1,1,0]
	s_waitcnt vmcnt(0)
	v_cndmask_b32_e32 v177, v178, v212, vcc
	v_pk_mul_f32 v[170:171], v[170:171], v[172:173]
	v_cndmask_b32_e32 v178, v179, v213, vcc
	v_pk_fma_f32 v[164:165], v[164:165], v[170:171], v[164:165]
	s_nop 0
	v_mul_f32_e32 v164, v114, v164
	v_mul_f32_e32 v170, v184, v164
	v_mul_f32_e32 v164, v115, v165
	v_mul_f32_e32 v165, v184, v164
	v_cvt_pk_bf16_f32 v164, v169, v182
	v_cvt_pk_bf16_f32 v165, v170, v165
	global_store_dwordx2 v[174:175], v[164:165], off
	v_mov_b32_dpp v169, v162 row_ror:2 row_mask:0xf bank_mask:0xf bound_ctrl:1
	v_mov_b32_dpp v165, v163 row_ror:1 row_mask:0xf bank_mask:0xf bound_ctrl:1
	v_mov_b32_dpp v170, v163 row_ror:2 row_mask:0xf bank_mask:0xf bound_ctrl:1
	v_mov_b32_dpp v164, v162 row_ror:1 row_mask:0xf bank_mask:0xf bound_ctrl:1
	v_mov_b32_dpp v165, v163 row_shr:1 row_mask:0xf bank_mask:0xf
	v_mov_b32_dpp v169, v162 row_shr:2 row_mask:0xf bank_mask:0xf
	v_mov_b32_dpp v170, v163 row_shr:2 row_mask:0xf bank_mask:0xf
	v_lshlrev_b32_e32 v172, 16, v165
	v_mov_b32_dpp v164, v162 row_shr:1 row_mask:0xf bank_mask:0xf
	v_lshlrev_b32_e32 v174, 16, v169
	v_and_b32_e32 v169, 0xffff0000, v169
	v_lshlrev_b32_e32 v175, 16, v170
	v_and_b32_e32 v176, 0xffff0000, v170
	v_cndmask_b32_e64 v170, v172, v214, s[0:1]
	v_cndmask_b32_e32 v172, v180, v214, vcc
	v_lshlrev_b32_e32 v171, 16, v164
	v_and_b32_e32 v164, 0xffff0000, v164
	v_and_b32_e32 v173, 0xffff0000, v165
	v_cndmask_b32_e64 v172, v175, v172, s[8:9]
	v_cndmask_b32_e64 v175, v169, v178, s[8:9]
	v_cndmask_b32_e64 v174, v174, v177, s[8:9]
	v_cndmask_b32_e64 v165, v164, v213, s[0:1]
	v_cndmask_b32_e64 v164, v171, v212, s[0:1]
	v_cndmask_b32_e64 v171, v173, v215, s[0:1]
	v_cndmask_b32_e32 v173, v181, v215, vcc
	v_pk_fma_f32 v[140:141], v[140:141], v[174:175], v[144:145]
	v_cndmask_b32_e64 v173, v176, v173, s[8:9]
	v_lshlrev_b32_e32 v176, 16, v162
	v_and_b32_e32 v177, 0xffff0000, v162
	v_pk_fma_f32 v[136:137], v[136:137], v[164:165], v[140:141]
	v_pk_fma_f32 v[142:143], v[142:143], v[172:173], v[146:147]
	v_pk_fma_f32 v[132:133], v[132:133], v[176:177], v[136:137]
	v_pk_fma_f32 v[138:139], v[138:139], v[170:171], v[142:143]
	v_pk_mul_f32 v[136:137], v[132:133], s[30:31] op_sel_hi:[1,0]
	v_pk_mul_f32 v[132:133], v[132:133], 0.5 op_sel_hi:[1,0]
	v_med3_f32 v136, v136, s47, v225
	v_med3_f32 v137, v137, s47, v225
	v_pk_mul_f32 v[140:141], v[136:137], v[136:137]
	s_nop 0
	v_pk_fma_f32 v[142:143], v[140:141], s[34:35], v[148:149] op_sel_hi:[1,0,0] neg_lo:[1,0,0] neg_hi:[1,0,0]
	s_nop 0
; __device__ __forceinline__ unsigned cvt_pk_bf16(float lo, float hi) { unsigned r; asm volatile("v_cvt_pk_bf16_f32 %0, %1, %2" : "=v"(r) : "v"(lo), "v"(hi)); return r; }
;     static __device__ __forceinline__ void finish(const float (&g0)[4], const float (&g1)[4], const float (&g2)[4], const float (&w0)[4], const float (&w1)[4], const float (&w2)[4], const float (&bb)[4],
;                                                   const f32x4 v, float rs, bf16_t* dst) {
;         float h[4];
; #pragma unroll
;         for (int j = 0; j < 4; j += 2) {
;             const f32x2 gc = (f32x2){bb[j] + w0[j] * g2[j] + w1[j] * g1[j] + w2[j] * g0[j], bb[j + 1] + w0[j + 1] * g2[j + 1] + w1[j + 1] * g1[j + 1] + w2[j + 1] * g0[j + 1]};
;             const f32x2 ge = gelu_pk(gc); h[j] = ge.x * v[j] * rs; h[j + 1] = ge.y * v[j + 1] * rs; }
;         u32x2 w; w.x = cvt_pk_bf16(h[0], h[1]); w.y = cvt_pk_bf16(h[2], h[3]);
;         *(u32x2*)dst = w;
;     }
;     __device__ __forceinline__ void operator()(const f32x4 (&acc)[2][2][4][2], const Unit& u, int wr, int wc, int fr, int fq) const {
;     ...
;         for (int bj = 0; bj < 2; ++bj)
; #pragma unroll
;           for (int hv = 0; hv < 2; ++hv) {
;             const int col = u.pn * BM + bj * HALF + wc * 32 + 8 * fq + 4 * hv;
;             float w0[4], w1[4], w2[4], bb[4];
;             ld4f(cw + col, w0); ld4f(cw + 2816 + col, w1); ld4f(cw + 2 * 2816 + col, w2); ld4f(cb + col, bb);
;             {
;                 const int i = fr & 7;
;                 u32x2 gq[4];
; #pragma unroll
;                 for (int m = 0; m < 4; ++m) { const int row = row0 + m * 16; gq[m] = *(const u32x2*)(G + (size_t)row * 2816 + col); }
; #pragma unroll
;                 for (int mh = 0; mh < 4; mh += 2) {
;                 f32x4 c0[4], c1[4];
; #pragma unroll
;                 for (int m = mh; m < mh + 2; ++m) { const int row = row0 + m * 16; const float* cx = ctx + (size_t)((row - 32768) >> 3) * 2 * 2816 + col;
;                     c0[m] = *(const f32x4*)cx; c1[m] = *(const f32x4*)(cx + 2816); }
	v_pk_fma_f32 v[142:143], v[140:141], v[142:143], s[38:39] op_sel_hi:[1,1,0]
	s_nop 0
	v_pk_fma_f32 v[142:143], v[140:141], v[142:143], s[40:41] op_sel_hi:[1,1,0]
	s_nop 0
	v_pk_fma_f32 v[142:143], v[140:141], v[142:143], s[42:43] op_sel_hi:[1,1,0]
	s_nop 0
	v_pk_fma_f32 v[142:143], v[140:141], v[142:143], s[44:45] op_sel_hi:[1,1,0]
	s_nop 0
	v_pk_fma_f32 v[142:143], v[140:141], v[142:143], s[46:47] op_sel_hi:[1,1,0]
	s_nop 0
	v_pk_fma_f32 v[140:141], v[140:141], v[142:143], s[48:49] op_sel_hi:[1,1,0]
	s_nop 0
	v_pk_mul_f32 v[136:137], v[136:137], v[140:141]
	s_nop 0
	v_pk_fma_f32 v[132:133], v[132:133], v[136:137], v[132:133]
	s_nop 0
	v_mul_f32_e32 v132, v104, v132
	v_mul_f32_e32 v140, v2, v132
	v_mul_f32_e32 v132, v105, v133
	v_mul_f32_e32 v141, v2, v132
	v_lshlrev_b32_e32 v132, 16, v163
	v_and_b32_e32 v133, 0xffff0000, v163
	v_pk_fma_f32 v[132:133], v[134:135], v[132:133], v[138:139]
	s_nop 0
	v_pk_mul_f32 v[134:135], v[132:133], s[30:31] op_sel_hi:[1,0]
	v_pk_mul_f32 v[132:133], v[132:133], 0.5 op_sel_hi:[1,0]
	v_med3_f32 v134, v134, s47, v225
	v_med3_f32 v135, v135, s47, v225
	v_pk_mul_f32 v[136:137], v[134:135], v[134:135]
	s_nop 0
	v_pk_fma_f32 v[138:139], v[136:137], s[34:35], v[148:149] op_sel_hi:[1,0,0] neg_lo:[1,0,0] neg_hi:[1,0,0]
	s_nop 0
	v_pk_fma_f32 v[138:139], v[136:137], v[138:139], s[38:39] op_sel_hi:[1,1,0]
	s_nop 0
	v_pk_fma_f32 v[138:139], v[136:137], v[138:139], s[40:41] op_sel_hi:[1,1,0]
	s_nop 0
	v_pk_fma_f32 v[138:139], v[136:137], v[138:139], s[42:43] op_sel_hi:[1,1,0]
	s_nop 0
	v_pk_fma_f32 v[138:139], v[136:137], v[138:139], s[44:45] op_sel_hi:[1,1,0]
	s_nop 0
	v_pk_fma_f32 v[138:139], v[136:137], v[138:139], s[46:47] op_sel_hi:[1,1,0]
	s_nop 0
	v_pk_fma_f32 v[136:137], v[136:137], v[138:139], s[48:49] op_sel_hi:[1,1,0]
	s_nop 0
	v_pk_mul_f32 v[134:135], v[134:135], v[136:137]
	s_nop 0
	v_pk_fma_f32 v[132:133], v[132:133], v[134:135], v[132:133]
	s_nop 0
	v_mul_f32_e32 v132, v106, v132
	v_mul_f32_e32 v134, v2, v132
	v_mul_f32_e32 v132, v107, v133
	v_mul_f32_e32 v133, v2, v132
	v_cvt_pk_bf16_f32 v132, v140, v141
	v_cvt_pk_bf16_f32 v133, v134, v133
	global_store_dwordx2 v[160:161], v[132:133], off
	v_add_u32_e32 v132, 4, v150
	v_ashrrev_i32_e32 v133, 31, v132
	v_lshlrev_b64 v[162:163], 1, v[132:133]
	v_lshl_add_u64 v[160:161], s[68:69], 0, v[162:163]
	v_lshlrev_b64 v[132:133], 2, v[132:133]
	v_mad_i64_i32 v[134:135], s[10:11], v210, s91, v[160:161]
	v_lshl_add_u64 v[226:227], s[82:83], 0, v[132:133]
	global_load_dwordx2 v[182:183], v[134:135], off
	v_mad_i64_i32 v[134:135], s[10:11], v151, s45, v[226:227]
	v_add_co_u32_e64 v136, s[10:11], s41, v134
	s_waitcnt vmcnt(0)
	v_mov_b32_dpp v169, v182 row_ror:1 row_mask:0xf bank_mask:0xf bound_ctrl:1
	v_addc_co_u32_e64 v137, s[10:11], 0, v135, s[10:11]
	global_load_dwordx4 v[170:173], v[136:137], off offset:3072
	global_load_dwordx4 v[174:177], v[134:135], off
	v_lshl_add_u64 v[134:135], s[66:67], 0, v[132:133]
	global_load_dwordx4 v[140:143], v[134:135], off
	v_lshl_add_u64 v[134:135], s[88:89], 0, v[132:133]
	global_load_dwordx4 v[144:147], v[134:135], off
	v_lshl_add_u64 v[134:135], s[52:53], 0, v[132:133]
	global_load_dwordx4 v[136:139], v[134:135], off
	v_lshl_add_u64 v[132:133], s[54:55], 0, v[132:133]
	global_load_dwordx4 v[132:135], v[132:133], off
	v_mad_i64_i32 v[164:165], s[10:11], v194, s91, v[160:161]
	v_mad_i64_i32 v[178:179], s[10:11], v192, s91, v[160:161]
	v_mad_i64_i32 v[160:161], s[10:11], v190, s91, v[160:161]
	global_load_dwordx2 v[228:229], v[164:165], off
	s_nop 0
	global_load_dwordx2 v[164:165], v[178:179], off
	s_nop 0
	global_load_dwordx2 v[160:161], v[160:161], off
	v_mad_i64_i32 v[178:179], s[10:11], v168, s45, v[226:227]
	v_add_co_u32_e64 v212, s[10:11], s41, v178
	v_mov_b32_dpp v169, v182 row_shr:1 row_mask:0xf bank_mask:0xf
	s_nop 0
	v_addc_co_u32_e64 v213, s[10:11], 0, v179, s[10:11]
	global_load_dwordx4 v[178:181], v[178:179], off
	s_nop 0
	global_load_dwordx4 v[212:215], v[212:213], off offset:3072
	v_mov_b32_dpp v185, v183 row_ror:1 row_mask:0xf bank_mask:0xf bound_ctrl:1
	v_mov_b32_dpp v187, v182 row_ror:2 row_mask:0xf bank_mask:0xf bound_ctrl:1
	v_lshlrev_b32_e32 v191, 16, v169
	v_mov_b32_dpp v185, v183 row_shr:1 row_mask:0xf bank_mask:0xf
	v_mov_b32_dpp v187, v182 row_shr:2 row_mask:0xf bank_mask:0xf
	v_and_b32_e32 v169, 0xffff0000, v169
	v_lshlrev_b32_e32 v193, 16, v185
	v_and_b32_e32 v185, 0xffff0000, v185
	v_lshlrev_b32_e32 v195, 16, v187
	v_and_b32_e32 v187, 0xffff0000, v187
	v_mov_b32_dpp v189, v183 row_ror:2 row_mask:0xf bank_mask:0xf bound_ctrl:1
	s_waitcnt vmcnt(10)
	v_cndmask_b32_e64 v231, v169, v171, s[0:1]
	s_waitcnt vmcnt(9)
	v_cndmask_b32_e32 v169, v174, v170, vcc
	v_cndmask_b32_e32 v174, v175, v171, vcc
	v_cndmask_b32_e64 v230, v191, v170, s[0:1]
	v_cndmask_b32_e64 v233, v185, v173, s[0:1]
	v_cndmask_b32_e64 v232, v193, v172, s[0:1]
	v_cndmask_b32_e32 v170, v176, v172, vcc
	v_cndmask_b32_e32 v171, v177, v173, vcc
	v_cndmask_b32_e64 v173, v187, v174, s[8:9]
	v_cndmask_b32_e64 v172, v195, v169, s[8:9]
	s_waitcnt vmcnt(7)
	v_pk_fma_f32 v[172:173], v[140:141], v[172:173], v[144:145]
	v_lshlrev_b32_e32 v176, 16, v182
	v_and_b32_e32 v177, 0xffff0000, v182
	s_waitcnt vmcnt(6)
	v_pk_fma_f32 v[172:173], v[136:137], v[230:231], v[172:173]
	v_mov_b32_dpp v189, v183 row_shr:2 row_mask:0xf bank_mask:0xf
	s_waitcnt vmcnt(5)
; __device__ __forceinline__ unsigned cvt_pk_bf16(float lo, float hi) { unsigned r; asm volatile("v_cvt_pk_bf16_f32 %0, %1, %2" : "=v"(r) : "v"(lo), "v"(hi)); return r; }
;     static __device__ __forceinline__ void unpk4(const u32x2 w, float (&o)[4]) { o[0] = bf_lo(w.x); o[1] = bf_hi(w.x); o[2] = bf_lo(w.y); o[3] = bf_hi(w.y); }
;     template <int N> static __device__ __forceinline__ u32x2 dpp_prev(const u32x2 pv, const u32x2 cur) { u32x2 r; r.x = dpp_prev1<N>(pv.x, cur.x); r.y = dpp_prev1<N>(pv.y, cur.y); return r; }
;     static __device__ __forceinline__ void finish(const float (&g0)[4], const float (&g1)[4], const float (&g2)[4], const float (&w0)[4], const float (&w1)[4], const float (&w2)[4], const float (&bb)[4],
;                                                   const f32x4 v, float rs, bf16_t* dst) {
;         float h[4];
; #pragma unroll
;         for (int j = 0; j < 4; j += 2) {
;             const f32x2 gc = (f32x2){bb[j] + w0[j] * g2[j] + w1[j] * g1[j] + w2[j] * g0[j], bb[j + 1] + w0[j + 1] * g2[j + 1] + w1[j + 1] * g1[j + 1] + w2[j + 1] * g0[j + 1]};
;             const f32x2 ge = gelu_pk(gc); h[j] = ge.x * v[j] * rs; h[j + 1] = ge.y * v[j + 1] * rs; }
;         u32x2 w; w.x = cvt_pk_bf16(h[0], h[1]); w.y = cvt_pk_bf16(h[2], h[3]);
;         *(u32x2*)dst = w;
;     }
;     __device__ __forceinline__ void operator()(const f32x4 (&acc)[2][2][4][2], const Unit& u, int wr, int wc, int fr, int fq) const {
;     ...
;                 for (int m = mh; m < mh + 2; ++m) { const int row = row0 + m * 16; const u32x2 cur = gq[m];
;                     const u32x2 q1 = dpp_prev<1>(cur, cur), q2 = dpp_prev<2>(cur, cur);
;                     float g0[4], g1[4], g2[4]; unpk4(cur, g0); unpk4(q1, g1); unpk4(q2, g2);
; #pragma unroll
;                     for (int j = 0; j < 4; ++j) { const float x1 = c1[m][j], x0 = c0[m][j];
;                         if (i < 1) g1[j] = x1;
;                         if (i < 2) g2[j] = (i == 1) ? x1 : x0; }
;                     finish(g0, g1, g2, w0, w1, w2, bb, acc[0][bj][m][hv], rs8[0][m], H + (size_t)row * 2816 + col); }
	v_pk_fma_f32 v[172:173], v[132:133], v[176:177], v[172:173]
	v_lshlrev_b32_e32 v211, 16, v189
	v_and_b32_e32 v189, 0xffff0000, v189
	v_pk_mul_f32 v[176:177], v[172:173], s[30:31] op_sel_hi:[1,0]
	v_cndmask_b32_e64 v171, v189, v171, s[8:9]
	v_cndmask_b32_e64 v170, v211, v170, s[8:9]
	v_med3_f32 v176, v176, s47, v225
	v_med3_f32 v177, v177, s47, v225
	v_pk_fma_f32 v[170:171], v[142:143], v[170:171], v[146:147]
	v_pk_mul_f32 v[230:231], v[176:177], v[176:177]
	v_pk_fma_f32 v[170:171], v[138:139], v[232:233], v[170:171]
	v_pk_fma_f32 v[232:233], v[230:231], s[34:35], v[148:149] op_sel_hi:[1,0,0] neg_lo:[1,0,0] neg_hi:[1,0,0]
	v_pk_mul_f32 v[172:173], v[172:173], 0.5 op_sel_hi:[1,0]
	v_pk_fma_f32 v[232:233], v[230:231], v[232:233], s[38:39] op_sel_hi:[1,1,0]
	v_lshl_add_u64 v[174:175], v[152:153], 0, v[162:163]
	v_pk_fma_f32 v[232:233], v[230:231], v[232:233], s[40:41] op_sel_hi:[1,1,0]
	s_nop 0
	v_pk_fma_f32 v[232:233], v[230:231], v[232:233], s[42:43] op_sel_hi:[1,1,0]
	s_nop 0
	v_pk_fma_f32 v[232:233], v[230:231], v[232:233], s[44:45] op_sel_hi:[1,1,0]
	s_nop 0
	v_pk_fma_f32 v[232:233], v[230:231], v[232:233], s[46:47] op_sel_hi:[1,1,0]
	s_nop 0
	v_pk_fma_f32 v[230:231], v[230:231], v[232:233], s[48:49] op_sel_hi:[1,1,0]
	s_nop 0
	v_pk_mul_f32 v[176:177], v[176:177], v[230:231]
	s_nop 0
	v_pk_fma_f32 v[172:173], v[172:173], v[176:177], v[172:173]
	s_nop 0
	v_mul_f32_e32 v169, v124, v172
	v_mul_f32_e32 v172, v125, v173
	v_mul_f32_e32 v185, v188, v172
	v_lshlrev_b32_e32 v172, 16, v183
	v_and_b32_e32 v173, 0xffff0000, v183
	v_pk_fma_f32 v[170:171], v[134:135], v[172:173], v[170:171]
	v_mul_f32_e32 v169, v188, v169
	v_pk_mul_f32 v[172:173], v[170:171], s[30:31] op_sel_hi:[1,0]
	v_pk_mul_f32 v[170:171], v[170:171], 0.5 op_sel_hi:[1,0]
	v_med3_f32 v172, v172, s47, v225
	v_med3_f32 v173, v173, s47, v225
	v_pk_mul_f32 v[176:177], v[172:173], v[172:173]
	s_nop 0
	v_pk_fma_f32 v[182:183], v[176:177], s[34:35], v[148:149] op_sel_hi:[1,0,0] neg_lo:[1,0,0] neg_hi:[1,0,0]
	s_nop 0
	v_pk_fma_f32 v[182:183], v[176:177], v[182:183], s[38:39] op_sel_hi:[1,1,0]
	s_nop 0
	v_pk_fma_f32 v[182:183], v[176:177], v[182:183], s[40:41] op_sel_hi:[1,1,0]
	s_nop 0
	v_pk_fma_f32 v[182:183], v[176:177], v[182:183], s[42:43] op_sel_hi:[1,1,0]
	s_nop 0
	v_pk_fma_f32 v[182:183], v[176:177], v[182:183], s[44:45] op_sel_hi:[1,1,0]
	s_nop 0
	v_pk_fma_f32 v[182:183], v[176:177], v[182:183], s[46:47] op_sel_hi:[1,1,0]
	s_nop 0
	v_pk_fma_f32 v[176:177], v[176:177], v[182:183], s[48:49] op_sel_hi:[1,1,0]
	s_nop 0
	v_pk_mul_f32 v[172:173], v[172:173], v[176:177]
	s_nop 0
	v_pk_fma_f32 v[170:171], v[170:171], v[172:173], v[170:171]
	s_nop 0
	v_mul_f32_e32 v170, v126, v170
	v_mul_f32_e32 v172, v188, v170
	v_mul_f32_e32 v170, v127, v171
	v_mul_f32_e32 v171, v188, v170
	v_cvt_pk_bf16_f32 v170, v169, v185
	v_cvt_pk_bf16_f32 v171, v172, v171
	s_waitcnt vmcnt(4)
	v_mov_b32_dpp v169, v228 row_ror:1 row_mask:0xf bank_mask:0xf bound_ctrl:1
	global_store_dwordx2 v[174:175], v[170:171], off
	v_mov_b32_dpp v171, v228 row_ror:2 row_mask:0xf bank_mask:0xf bound_ctrl:1
	v_mov_b32_dpp v169, v228 row_shr:1 row_mask:0xf bank_mask:0xf
	v_mov_b32_dpp v170, v229 row_ror:1 row_mask:0xf bank_mask:0xf bound_ctrl:1
	v_mov_b32_dpp v171, v228 row_shr:2 row_mask:0xf bank_mask:0xf
	v_lshlrev_b32_e32 v173, 16, v169
	v_and_b32_e32 v169, 0xffff0000, v169
	v_mov_b32_dpp v170, v229 row_shr:1 row_mask:0xf bank_mask:0xf
	v_mov_b32_dpp v172, v229 row_ror:2 row_mask:0xf bank_mask:0xf bound_ctrl:1
	v_lshlrev_b32_e32 v176, 16, v171
	v_and_b32_e32 v177, 0xffff0000, v171
	s_waitcnt vmcnt(1)
	v_cndmask_b32_e64 v171, v169, v213, s[0:1]
	v_cndmask_b32_e32 v169, v178, v212, vcc
	v_cndmask_b32_e32 v178, v179, v213, vcc
	v_mov_b32_dpp v172, v229 row_shr:2 row_mask:0xf bank_mask:0xf
	v_lshlrev_b32_e32 v174, 16, v170
	v_and_b32_e32 v175, 0xffff0000, v170
	v_cndmask_b32_e64 v177, v177, v178, s[8:9]
	v_cndmask_b32_e64 v176, v176, v169, s[8:9]
	v_lshlrev_b32_e32 v182, 16, v172
	v_and_b32_e32 v183, 0xffff0000, v172
	v_cndmask_b32_e64 v170, v173, v212, s[0:1]
	v_cndmask_b32_e64 v173, v175, v215, s[0:1]
	v_cndmask_b32_e64 v172, v174, v214, s[0:1]
	v_cndmask_b32_e32 v174, v180, v214, vcc
	v_cndmask_b32_e32 v175, v181, v215, vcc
	v_pk_fma_f32 v[176:177], v[140:141], v[176:177], v[144:145]
	v_cndmask_b32_e64 v175, v183, v175, s[8:9]
	v_cndmask_b32_e64 v174, v182, v174, s[8:9]
	v_lshlrev_b32_e32 v180, 16, v228
	v_and_b32_e32 v181, 0xffff0000, v228
	v_pk_fma_f32 v[170:171], v[136:137], v[170:171], v[176:177]
	v_pk_fma_f32 v[174:175], v[142:143], v[174:175], v[146:147]
	v_pk_fma_f32 v[170:171], v[132:133], v[180:181], v[170:171]
	v_pk_fma_f32 v[172:173], v[138:139], v[172:173], v[174:175]
	v_pk_mul_f32 v[174:175], v[170:171], s[30:31] op_sel_hi:[1,0]
	v_pk_mul_f32 v[170:171], v[170:171], 0.5 op_sel_hi:[1,0]
	v_med3_f32 v174, v174, s47, v225
	v_med3_f32 v175, v175, s47, v225
	v_pk_mul_f32 v[176:177], v[174:175], v[174:175]
	v_lshl_add_u64 v[178:179], v[154:155], 0, v[162:163]
	v_pk_fma_f32 v[180:181], v[176:177], s[34:35], v[148:149] op_sel_hi:[1,0,0] neg_lo:[1,0,0] neg_hi:[1,0,0]
	v_mov_b32_dpp v185, v165 row_ror:2 row_mask:0xf bank_mask:0xf bound_ctrl:1
	v_pk_fma_f32 v[180:181], v[176:177], v[180:181], s[38:39] op_sel_hi:[1,1,0]
	s_nop 0
	v_pk_fma_f32 v[180:181], v[176:177], v[180:181], s[40:41] op_sel_hi:[1,1,0]
	v_mov_b32_dpp v185, v165 row_shr:2 row_mask:0xf bank_mask:0xf
	v_pk_fma_f32 v[180:181], v[176:177], v[180:181], s[42:43] op_sel_hi:[1,1,0]
	v_lshlrev_b32_e32 v211, 16, v185
	v_pk_fma_f32 v[180:181], v[176:177], v[180:181], s[44:45] op_sel_hi:[1,1,0]
	v_and_b32_e32 v185, 0xffff0000, v185
	v_pk_fma_f32 v[180:181], v[176:177], v[180:181], s[46:47] op_sel_hi:[1,1,0]
; __device__ __forceinline__ unsigned cvt_pk_bf16(float lo, float hi) { unsigned r; asm volatile("v_cvt_pk_bf16_f32 %0, %1, %2" : "=v"(r) : "v"(lo), "v"(hi)); return r; }
;     static __device__ __forceinline__ void unpk4(const u32x2 w, float (&o)[4]) { o[0] = bf_lo(w.x); o[1] = bf_hi(w.x); o[2] = bf_lo(w.y); o[3] = bf_hi(w.y); }
;     template <int N> static __device__ __forceinline__ u32x2 dpp_prev(const u32x2 pv, const u32x2 cur) { u32x2 r; r.x = dpp_prev1<N>(pv.x, cur.x); r.y = dpp_prev1<N>(pv.y, cur.y); return r; }
;     static __device__ __forceinline__ void finish(const float (&g0)[4], const float (&g1)[4], const float (&g2)[4], const float (&w0)[4], const float (&w1)[4], const float (&w2)[4], const float (&bb)[4],
;                                                   const f32x4 v, float rs, bf16_t* dst) {
;         float h[4];
; #pragma unroll
;         for (int j = 0; j < 4; j += 2) {
;             const f32x2 gc = (f32x2){bb[j] + w0[j] * g2[j] + w1[j] * g1[j] + w2[j] * g0[j], bb[j + 1] + w0[j + 1] * g2[j + 1] + w1[j + 1] * g1[j + 1] + w2[j + 1] * g0[j + 1]};
;             const f32x2 ge = gelu_pk(gc); h[j] = ge.x * v[j] * rs; h[j + 1] = ge.y * v[j + 1] * rs; }
;         u32x2 w; w.x = cvt_pk_bf16(h[0], h[1]); w.y = cvt_pk_bf16(h[2], h[3]);
;         *(u32x2*)dst = w;
;     }
;     __device__ __forceinline__ void operator()(const f32x4 (&acc)[2][2][4][2], const Unit& u, int wr, int wc, int fr, int fq) const {
;     ...
;                 for (int m = mh; m < mh + 2; ++m) { const int row = row0 + m * 16; const float* cx = ctx + (size_t)((row - 32768) >> 3) * 2 * 2816 + col;
;                     c0[m] = *(const f32x4*)cx; c1[m] = *(const f32x4*)(cx + 2816); }
; #pragma unroll
;                 for (int m = mh; m < mh + 2; ++m) { const int row = row0 + m * 16; const u32x2 cur = gq[m];
;                     const u32x2 q1 = dpp_prev<1>(cur, cur), q2 = dpp_prev<2>(cur, cur);
;                     float g0[4], g1[4], g2[4]; unpk4(cur, g0); unpk4(q1, g1); unpk4(q2, g2);
; #pragma unroll
;                     for (int j = 0; j < 4; ++j) { const float x1 = c1[m][j], x0 = c0[m][j];
;                         if (i < 1) g1[j] = x1;
;                         if (i < 2) g2[j] = (i == 1) ? x1 : x0; }
;                     finish(g0, g1, g2, w0, w1, w2, bb, acc[0][bj][m][hv], rs8[0][m], H + (size_t)row * 2816 + col); }
	s_nop 0
	v_pk_fma_f32 v[176:177], v[176:177], v[180:181], s[48:49] op_sel_hi:[1,1,0]
	s_nop 0
	v_pk_mul_f32 v[174:175], v[174:175], v[176:177]
	s_nop 0
	v_pk_fma_f32 v[170:171], v[170:171], v[174:175], v[170:171]
	s_nop 0
	v_mul_f32_e32 v169, v116, v170
	v_mul_f32_e32 v170, v117, v171
	v_mul_f32_e32 v180, v186, v170
	v_lshlrev_b32_e32 v170, 16, v229
	v_and_b32_e32 v171, 0xffff0000, v229
	v_pk_fma_f32 v[170:171], v[134:135], v[170:171], v[172:173]
	v_mul_f32_e32 v169, v186, v169
	v_pk_mul_f32 v[172:173], v[170:171], s[30:31] op_sel_hi:[1,0]
	v_pk_mul_f32 v[170:171], v[170:171], 0.5 op_sel_hi:[1,0]
	v_med3_f32 v172, v172, s47, v225
	v_med3_f32 v173, v173, s47, v225
	v_pk_mul_f32 v[174:175], v[172:173], v[172:173]
	s_nop 0
	v_pk_fma_f32 v[176:177], v[174:175], s[34:35], v[148:149] op_sel_hi:[1,0,0] neg_lo:[1,0,0] neg_hi:[1,0,0]
	s_nop 0
	v_pk_fma_f32 v[176:177], v[174:175], v[176:177], s[38:39] op_sel_hi:[1,1,0]
	s_nop 0
	v_pk_fma_f32 v[176:177], v[174:175], v[176:177], s[40:41] op_sel_hi:[1,1,0]
	s_nop 0
	v_pk_fma_f32 v[176:177], v[174:175], v[176:177], s[42:43] op_sel_hi:[1,1,0]
	s_nop 0
	v_pk_fma_f32 v[176:177], v[174:175], v[176:177], s[44:45] op_sel_hi:[1,1,0]
	s_nop 0
	v_pk_fma_f32 v[176:177], v[174:175], v[176:177], s[46:47] op_sel_hi:[1,1,0]
	s_nop 0
	v_pk_fma_f32 v[174:175], v[174:175], v[176:177], s[48:49] op_sel_hi:[1,1,0]
	s_nop 0
	v_pk_mul_f32 v[172:173], v[172:173], v[174:175]
	v_mad_i64_i32 v[174:175], s[10:11], v166, s45, v[226:227]
	v_pk_fma_f32 v[170:171], v[170:171], v[172:173], v[170:171]
	s_nop 0
	v_mul_f32_e32 v170, v118, v170
	v_mul_f32_e32 v172, v186, v170
	v_mul_f32_e32 v170, v119, v171
	v_mul_f32_e32 v171, v186, v170
	v_cvt_pk_bf16_f32 v170, v169, v180
	v_cvt_pk_bf16_f32 v171, v172, v171
	global_store_dwordx2 v[178:179], v[170:171], off
	v_add_co_u32_e64 v170, s[10:11], s41, v174
	v_mov_b32_dpp v169, v164 row_ror:1 row_mask:0xf bank_mask:0xf bound_ctrl:1
	s_nop 0
	v_addc_co_u32_e64 v171, s[10:11], 0, v175, s[10:11]
	global_load_dwordx4 v[170:173], v[170:171], off offset:3072
	s_nop 0
	global_load_dwordx4 v[174:177], v[174:175], off
	v_mad_i64_i32 v[178:179], s[10:11], v167, s45, v[226:227]
	v_add_co_u32_e64 v182, s[10:11], s41, v178
	v_mov_b32_dpp v169, v164 row_shr:1 row_mask:0xf bank_mask:0xf
	s_nop 0
	v_addc_co_u32_e64 v183, s[10:11], 0, v179, s[10:11]
	global_load_dwordx4 v[178:181], v[178:179], off
	s_nop 0
	global_load_dwordx4 v[212:215], v[182:183], off offset:3072
	v_mov_b32_dpp v182, v165 row_ror:1 row_mask:0xf bank_mask:0xf bound_ctrl:1
	v_mov_b32_dpp v183, v164 row_ror:2 row_mask:0xf bank_mask:0xf bound_ctrl:1
	v_lshlrev_b32_e32 v187, 16, v169
	v_mov_b32_dpp v182, v165 row_shr:1 row_mask:0xf bank_mask:0xf
	v_mov_b32_dpp v183, v164 row_shr:2 row_mask:0xf bank_mask:0xf
	v_and_b32_e32 v169, 0xffff0000, v169
	v_lshlrev_b32_e32 v189, 16, v182
	v_and_b32_e32 v191, 0xffff0000, v182
	v_lshlrev_b32_e32 v193, 16, v183
	v_and_b32_e32 v195, 0xffff0000, v183
	s_waitcnt vmcnt(3)
	v_cndmask_b32_e64 v183, v169, v171, s[0:1]
	s_waitcnt vmcnt(2)
	v_cndmask_b32_e32 v169, v174, v170, vcc
	v_cndmask_b32_e32 v174, v175, v171, vcc
	v_cndmask_b32_e64 v182, v187, v170, s[0:1]
	v_cndmask_b32_e64 v227, v191, v173, s[0:1]
	v_cndmask_b32_e64 v226, v189, v172, s[0:1]
	v_cndmask_b32_e32 v170, v176, v172, vcc
	v_cndmask_b32_e32 v171, v177, v173, vcc
	v_cndmask_b32_e64 v173, v195, v174, s[8:9]
	v_cndmask_b32_e64 v172, v193, v169, s[8:9]
	v_pk_fma_f32 v[172:173], v[140:141], v[172:173], v[144:145]
	v_lshlrev_b32_e32 v176, 16, v164
	v_and_b32_e32 v177, 0xffff0000, v164
	v_pk_fma_f32 v[172:173], v[136:137], v[182:183], v[172:173]
	v_cndmask_b32_e64 v171, v185, v171, s[8:9]
	v_pk_fma_f32 v[172:173], v[132:133], v[176:177], v[172:173]
	v_cndmask_b32_e64 v170, v211, v170, s[8:9]
	v_pk_mul_f32 v[176:177], v[172:173], s[30:31] op_sel_hi:[1,0]
	v_pk_fma_f32 v[170:171], v[142:143], v[170:171], v[146:147]
	v_med3_f32 v176, v176, s47, v225
	v_med3_f32 v177, v177, s47, v225
	v_pk_mul_f32 v[182:183], v[176:177], v[176:177]
	v_pk_fma_f32 v[170:171], v[138:139], v[226:227], v[170:171]
	v_pk_fma_f32 v[226:227], v[182:183], s[34:35], v[148:149] op_sel_hi:[1,0,0] neg_lo:[1,0,0] neg_hi:[1,0,0]
	v_pk_mul_f32 v[172:173], v[172:173], 0.5 op_sel_hi:[1,0]
	v_pk_fma_f32 v[226:227], v[182:183], v[226:227], s[38:39] op_sel_hi:[1,1,0]
	v_lshl_add_u64 v[174:175], v[156:157], 0, v[162:163]
	v_pk_fma_f32 v[226:227], v[182:183], v[226:227], s[40:41] op_sel_hi:[1,1,0]
	v_lshl_add_u64 v[162:163], v[158:159], 0, v[162:163]
	v_pk_fma_f32 v[226:227], v[182:183], v[226:227], s[42:43] op_sel_hi:[1,1,0]
	s_nop 0
	v_pk_fma_f32 v[226:227], v[182:183], v[226:227], s[44:45] op_sel_hi:[1,1,0]
	s_nop 0
	v_pk_fma_f32 v[226:227], v[182:183], v[226:227], s[46:47] op_sel_hi:[1,1,0]
	s_nop 0
	v_pk_fma_f32 v[182:183], v[182:183], v[226:227], s[48:49] op_sel_hi:[1,1,0]
	s_nop 0
	v_pk_mul_f32 v[176:177], v[176:177], v[182:183]
	s_nop 0
	v_pk_fma_f32 v[172:173], v[172:173], v[176:177], v[172:173]
	s_nop 0
	v_mul_f32_e32 v164, v108, v172
	v_mul_f32_e32 v169, v184, v164
	v_mul_f32_e32 v164, v109, v173
	v_mul_f32_e32 v182, v184, v164
	v_lshlrev_b32_e32 v164, 16, v165
	v_and_b32_e32 v165, 0xffff0000, v165
	v_pk_fma_f32 v[164:165], v[134:135], v[164:165], v[170:171]
	s_nop 0
	v_pk_mul_f32 v[170:171], v[164:165], s[30:31] op_sel_hi:[1,0]
	v_pk_mul_f32 v[164:165], v[164:165], 0.5 op_sel_hi:[1,0]
	v_med3_f32 v170, v170, s47, v225
	v_med3_f32 v171, v171, s47, v225
	v_pk_mul_f32 v[172:173], v[170:171], v[170:171]
	s_nop 0
	v_pk_fma_f32 v[176:177], v[172:173], s[34:35], v[148:149] op_sel_hi:[1,0,0] neg_lo:[1,0,0] neg_hi:[1,0,0]
	s_nop 0
	v_pk_fma_f32 v[176:177], v[172:173], v[176:177], s[38:39] op_sel_hi:[1,1,0]
	s_nop 0
	v_pk_fma_f32 v[176:177], v[172:173], v[176:177], s[40:41] op_sel_hi:[1,1,0]
	s_nop 0
	v_pk_fma_f32 v[176:177], v[172:173], v[176:177], s[42:43] op_sel_hi:[1,1,0]
	s_nop 0
	v_pk_fma_f32 v[176:177], v[172:173], v[176:177], s[44:45] op_sel_hi:[1,1,0]
	s_nop 0
	v_pk_fma_f32 v[176:177], v[172:173], v[176:177], s[46:47] op_sel_hi:[1,1,0]
	s_nop 0
	v_pk_fma_f32 v[172:173], v[172:173], v[176:177], s[48:49] op_sel_hi:[1,1,0]
	s_waitcnt vmcnt(0)
;     static __device__ __forceinline__ void finish(const float (&g0)[4], const float (&g1)[4], const float (&g2)[4], const float (&w0)[4], const float (&w1)[4], const float (&w2)[4], const float (&bb)[4],
;                                                   const f32x4 v, float rs, bf16_t* dst) {
;         float h[4];
; #pragma unroll
;         for (int j = 0; j < 4; j += 2) {
;             const f32x2 gc = (f32x2){bb[j] + w0[j] * g2[j] + w1[j] * g1[j] + w2[j] * g0[j], bb[j + 1] + w0[j + 1] * g2[j + 1] + w1[j + 1] * g1[j + 1] + w2[j + 1] * g0[j + 1]};
;     __device__ __forceinline__ void operator()(const f32x4 (&acc)[2][2][4][2], const Unit& u, int wr, int wc, int fr, int fq) const {
;     ...
;         for (int bj = 0; bj < 2; ++bj)
; #pragma unroll
;           for (int hv = 0; hv < 2; ++hv) {
;             const int col = u.pn * BM + bj * HALF + wc * 32 + 8 * fq + 4 * hv;
;             float w0[4], w1[4], w2[4], bb[4];
;             ld4f(cw + col, w0); ld4f(cw + 2816 + col, w1); ld4f(cw + 2 * 2816 + col, w2); ld4f(cb + col, bb);
;             {
;                 const int i = fr & 7;
;                 u32x2 gq[4];
; #pragma unroll
;                 for (int m = 0; m < 4; ++m) { const int row = row0 + m * 16; gq[m] = *(const u32x2*)(G + (size_t)row * 2816 + col); }
; #pragma unroll
;                 for (int mh = 0; mh < 4; mh += 2) {
;                 f32x4 c0[4], c1[4];
; #pragma unroll
;                 for (int m = mh; m < mh + 2; ++m) { const int row = row0 + m * 16; const float* cx = ctx + (size_t)((row - 32768) >> 3) * 2 * 2816 + col;
;                     c0[m] = *(const f32x4*)cx; c1[m] = *(const f32x4*)(cx + 2816); }
; #pragma unroll
;                 for (int m = mh; m < mh + 2; ++m) { const int row = row0 + m * 16; const u32x2 cur = gq[m];
;                     const u32x2 q1 = dpp_prev<1>(cur, cur), q2 = dpp_prev<2>(cur, cur);
;                     float g0[4], g1[4], g2[4]; unpk4(cur, g0); unpk4(q1, g1); unpk4(q2, g2);
; #pragma unroll
;                     for (int j = 0; j < 4; ++j) { const float x1 = c1[m][j], x0 = c0[m][j];
;                         if (i < 1) g1[j] = x1;
;                         if (i < 2) g2[j] = (i == 1) ? x1 : x0; }
;                     finish(g0, g1, g2, w0, w1, w2, bb, acc[0][bj][m][hv], rs8[0][m], H + (size_t)row * 2816 + col); }
	v_cndmask_b32_e32 v177, v178, v212, vcc
	v_pk_mul_f32 v[170:171], v[170:171], v[172:173]
	v_cndmask_b32_e32 v178, v179, v213, vcc
	v_pk_fma_f32 v[164:165], v[164:165], v[170:171], v[164:165]
	s_nop 0
	v_mul_f32_e32 v164, v110, v164
	v_mul_f32_e32 v170, v184, v164
	v_mul_f32_e32 v164, v111, v165
	v_mul_f32_e32 v165, v184, v164
	v_cvt_pk_bf16_f32 v164, v169, v182
	v_cvt_pk_bf16_f32 v165, v170, v165
	global_store_dwordx2 v[174:175], v[164:165], off
	v_mov_b32_dpp v169, v160 row_ror:2 row_mask:0xf bank_mask:0xf bound_ctrl:1
	v_mov_b32_dpp v165, v161 row_ror:1 row_mask:0xf bank_mask:0xf bound_ctrl:1
	v_mov_b32_dpp v170, v161 row_ror:2 row_mask:0xf bank_mask:0xf bound_ctrl:1
	v_mov_b32_dpp v164, v160 row_ror:1 row_mask:0xf bank_mask:0xf bound_ctrl:1
	v_mov_b32_dpp v165, v161 row_shr:1 row_mask:0xf bank_mask:0xf
	v_mov_b32_dpp v169, v160 row_shr:2 row_mask:0xf bank_mask:0xf
	v_mov_b32_dpp v170, v161 row_shr:2 row_mask:0xf bank_mask:0xf
	v_lshlrev_b32_e32 v172, 16, v165
	v_mov_b32_dpp v164, v160 row_shr:1 row_mask:0xf bank_mask:0xf
	v_lshlrev_b32_e32 v174, 16, v169
	v_and_b32_e32 v169, 0xffff0000, v169
	v_lshlrev_b32_e32 v175, 16, v170
	v_and_b32_e32 v176, 0xffff0000, v170
	v_cndmask_b32_e64 v170, v172, v214, s[0:1]
	v_cndmask_b32_e32 v172, v180, v214, vcc
	v_lshlrev_b32_e32 v171, 16, v164
	v_and_b32_e32 v164, 0xffff0000, v164
	v_and_b32_e32 v173, 0xffff0000, v165
	v_cndmask_b32_e64 v172, v175, v172, s[8:9]
	v_cndmask_b32_e64 v175, v169, v178, s[8:9]
	v_cndmask_b32_e64 v174, v174, v177, s[8:9]
	v_cndmask_b32_e64 v165, v164, v213, s[0:1]
	v_cndmask_b32_e64 v164, v171, v212, s[0:1]
	v_cndmask_b32_e64 v171, v173, v215, s[0:1]
	v_cndmask_b32_e32 v173, v181, v215, vcc
	v_pk_fma_f32 v[140:141], v[140:141], v[174:175], v[144:145]
	v_cndmask_b32_e64 v173, v176, v173, s[8:9]
	v_lshlrev_b32_e32 v176, 16, v160
	v_and_b32_e32 v177, 0xffff0000, v160
	v_pk_fma_f32 v[136:137], v[136:137], v[164:165], v[140:141]
	v_pk_fma_f32 v[142:143], v[142:143], v[172:173], v[146:147]
	v_pk_fma_f32 v[132:133], v[132:133], v[176:177], v[136:137]
	v_pk_fma_f32 v[138:139], v[138:139], v[170:171], v[142:143]
	v_pk_mul_f32 v[136:137], v[132:133], s[30:31] op_sel_hi:[1,0]
	v_pk_mul_f32 v[132:133], v[132:133], 0.5 op_sel_hi:[1,0]
	v_med3_f32 v136, v136, s47, v225
	v_med3_f32 v137, v137, s47, v225
	v_pk_mul_f32 v[140:141], v[136:137], v[136:137]
	s_nop 0
	v_pk_fma_f32 v[142:143], v[140:141], s[34:35], v[148:149] op_sel_hi:[1,0,0] neg_lo:[1,0,0] neg_hi:[1,0,0]
	s_nop 0
	v_pk_fma_f32 v[142:143], v[140:141], v[142:143], s[38:39] op_sel_hi:[1,1,0]
	s_nop 0
	v_pk_fma_f32 v[142:143], v[140:141], v[142:143], s[40:41] op_sel_hi:[1,1,0]
	s_nop 0
	v_pk_fma_f32 v[142:143], v[140:141], v[142:143], s[42:43] op_sel_hi:[1,1,0]
	s_nop 0
	v_pk_fma_f32 v[142:143], v[140:141], v[142:143], s[44:45] op_sel_hi:[1,1,0]
	s_nop 0
	v_pk_fma_f32 v[142:143], v[140:141], v[142:143], s[46:47] op_sel_hi:[1,1,0]
	s_nop 0
	v_pk_fma_f32 v[140:141], v[140:141], v[142:143], s[48:49] op_sel_hi:[1,1,0]
	s_nop 0
	v_pk_mul_f32 v[136:137], v[136:137], v[140:141]
	s_nop 0
	v_pk_fma_f32 v[132:133], v[132:133], v[136:137], v[132:133]
	s_nop 0
	v_mul_f32_e32 v132, v100, v132
	v_mul_f32_e32 v140, v2, v132
	v_mul_f32_e32 v132, v101, v133
	v_mul_f32_e32 v141, v2, v132
	v_lshlrev_b32_e32 v132, 16, v161
	v_and_b32_e32 v133, 0xffff0000, v161
	v_pk_fma_f32 v[132:133], v[134:135], v[132:133], v[138:139]
	s_nop 0
	v_pk_mul_f32 v[134:135], v[132:133], s[30:31] op_sel_hi:[1,0]
	v_pk_mul_f32 v[132:133], v[132:133], 0.5 op_sel_hi:[1,0]
	v_med3_f32 v134, v134, s47, v225
	v_med3_f32 v135, v135, s47, v225
	v_pk_mul_f32 v[136:137], v[134:135], v[134:135]
	s_nop 0
	v_pk_fma_f32 v[138:139], v[136:137], s[34:35], v[148:149] op_sel_hi:[1,0,0] neg_lo:[1,0,0] neg_hi:[1,0,0]
	s_nop 0
	v_pk_fma_f32 v[138:139], v[136:137], v[138:139], s[38:39] op_sel_hi:[1,1,0]
	s_nop 0
	v_pk_fma_f32 v[138:139], v[136:137], v[138:139], s[40:41] op_sel_hi:[1,1,0]
	s_nop 0
	v_pk_fma_f32 v[138:139], v[136:137], v[138:139], s[42:43] op_sel_hi:[1,1,0]
	s_nop 0
	v_pk_fma_f32 v[138:139], v[136:137], v[138:139], s[44:45] op_sel_hi:[1,1,0]
	s_nop 0
	v_pk_fma_f32 v[138:139], v[136:137], v[138:139], s[46:47] op_sel_hi:[1,1,0]
	s_nop 0
	v_pk_fma_f32 v[136:137], v[136:137], v[138:139], s[48:49] op_sel_hi:[1,1,0]
	s_nop 0
	v_pk_mul_f32 v[134:135], v[134:135], v[136:137]
	s_nop 0
	v_pk_fma_f32 v[132:133], v[132:133], v[134:135], v[132:133]
	s_nop 0
	v_mul_f32_e32 v132, v102, v132
	v_mul_f32_e32 v134, v2, v132
	v_mul_f32_e32 v132, v103, v133
	v_mul_f32_e32 v133, v2, v132
	v_cvt_pk_bf16_f32 v132, v140, v141
	v_cvt_pk_bf16_f32 v133, v134, v133
	global_store_dwordx2 v[162:163], v[132:133], off
	v_add_u32_e32 v132, 0x80, v150
	v_ashrrev_i32_e32 v133, 31, v132
	v_lshlrev_b64 v[162:163], 1, v[132:133]
	v_lshl_add_u64 v[160:161], s[68:69], 0, v[162:163]
	v_lshlrev_b64 v[132:133], 2, v[132:133]
	v_mad_i64_i32 v[134:135], s[10:11], v210, s91, v[160:161]
	v_lshl_add_u64 v[226:227], s[82:83], 0, v[132:133]
	global_load_dwordx2 v[182:183], v[134:135], off
	v_mad_i64_i32 v[134:135], s[10:11], v151, s45, v[226:227]
	v_add_co_u32_e64 v136, s[10:11], s41, v134
	s_waitcnt vmcnt(0)
;     static __device__ __forceinline__ void finish(const float (&g0)[4], const float (&g1)[4], const float (&g2)[4], const float (&w0)[4], const float (&w1)[4], const float (&w2)[4], const float (&bb)[4],
;                                                   const f32x4 v, float rs, bf16_t* dst) {
;         float h[4];
; #pragma unroll
;         for (int j = 0; j < 4; j += 2) {
;             const f32x2 gc = (f32x2){bb[j] + w0[j] * g2[j] + w1[j] * g1[j] + w2[j] * g0[j], bb[j + 1] + w0[j + 1] * g2[j + 1] + w1[j + 1] * g1[j + 1] + w2[j + 1] * g0[j + 1]};
;             const f32x2 ge = gelu_pk(gc); h[j] = ge.x * v[j] * rs; h[j + 1] = ge.y * v[j + 1] * rs; }
;         u32x2 w; w.x = cvt_pk_bf16(h[0], h[1]); w.y = cvt_pk_bf16(h[2], h[3]);
;     __device__ __forceinline__ void operator()(const f32x4 (&acc)[2][2][4][2], const Unit& u, int wr, int wc, int fr, int fq) const {
;     ...
;             const int col = u.pn * BM + bj * HALF + wc * 32 + 8 * fq + 4 * hv;
;             float w0[4], w1[4], w2[4], bb[4];
;             ld4f(cw + col, w0); ld4f(cw + 2816 + col, w1); ld4f(cw + 2 * 2816 + col, w2); ld4f(cb + col, bb);
;             {
;                 const int i = fr & 7;
;                 u32x2 gq[4];
; #pragma unroll
;                 for (int m = 0; m < 4; ++m) { const int row = row0 + m * 16; gq[m] = *(const u32x2*)(G + (size_t)row * 2816 + col); }
; #pragma unroll
;                 for (int mh = 0; mh < 4; mh += 2) {
;                 f32x4 c0[4], c1[4];
; #pragma unroll
;                 for (int m = mh; m < mh + 2; ++m) { const int row = row0 + m * 16; const float* cx = ctx + (size_t)((row - 32768) >> 3) * 2 * 2816 + col;
;                     c0[m] = *(const f32x4*)cx; c1[m] = *(const f32x4*)(cx + 2816); }
; #pragma unroll
;                 for (int m = mh; m < mh + 2; ++m) { const int row = row0 + m * 16; const u32x2 cur = gq[m];
;                     const u32x2 q1 = dpp_prev<1>(cur, cur), q2 = dpp_prev<2>(cur, cur);
;                     float g0[4], g1[4], g2[4]; unpk4(cur, g0); unpk4(q1, g1); unpk4(q2, g2);
; #pragma unroll
;                     for (int j = 0; j < 4; ++j) { const float x1 = c1[m][j], x0 = c0[m][j];
;                         if (i < 1) g1[j] = x1;
;                         if (i < 2) g2[j] = (i == 1) ? x1 : x0; }
;                     finish(g0, g1, g2, w0, w1, w2, bb, acc[0][bj][m][hv], rs8[0][m], H + (size_t)row * 2816 + col); }
	v_mov_b32_dpp v169, v182 row_ror:1 row_mask:0xf bank_mask:0xf bound_ctrl:1
	v_addc_co_u32_e64 v137, s[10:11], 0, v135, s[10:11]
	global_load_dwordx4 v[170:173], v[136:137], off offset:3072
	global_load_dwordx4 v[174:177], v[134:135], off
	v_lshl_add_u64 v[134:135], s[66:67], 0, v[132:133]
	global_load_dwordx4 v[140:143], v[134:135], off
	v_lshl_add_u64 v[134:135], s[88:89], 0, v[132:133]
	global_load_dwordx4 v[144:147], v[134:135], off
	v_lshl_add_u64 v[134:135], s[52:53], 0, v[132:133]
	global_load_dwordx4 v[136:139], v[134:135], off
	v_lshl_add_u64 v[132:133], s[54:55], 0, v[132:133]
	global_load_dwordx4 v[132:135], v[132:133], off
	v_mad_i64_i32 v[164:165], s[10:11], v194, s91, v[160:161]
	v_mad_i64_i32 v[178:179], s[10:11], v192, s91, v[160:161]
	v_mad_i64_i32 v[160:161], s[10:11], v190, s91, v[160:161]
	global_load_dwordx2 v[228:229], v[164:165], off
	s_nop 0
	global_load_dwordx2 v[164:165], v[178:179], off
	s_nop 0
	global_load_dwordx2 v[160:161], v[160:161], off
	v_mad_i64_i32 v[178:179], s[10:11], v168, s45, v[226:227]
	v_add_co_u32_e64 v212, s[10:11], s41, v178
	v_mov_b32_dpp v169, v182 row_shr:1 row_mask:0xf bank_mask:0xf
	s_nop 0
	v_addc_co_u32_e64 v213, s[10:11], 0, v179, s[10:11]
	global_load_dwordx4 v[178:181], v[178:179], off
	s_nop 0
	global_load_dwordx4 v[212:215], v[212:213], off offset:3072
	v_mov_b32_dpp v185, v183 row_ror:1 row_mask:0xf bank_mask:0xf bound_ctrl:1
	v_mov_b32_dpp v187, v182 row_ror:2 row_mask:0xf bank_mask:0xf bound_ctrl:1
	v_lshlrev_b32_e32 v191, 16, v169
	v_mov_b32_dpp v185, v183 row_shr:1 row_mask:0xf bank_mask:0xf
	v_mov_b32_dpp v187, v182 row_shr:2 row_mask:0xf bank_mask:0xf
	v_and_b32_e32 v169, 0xffff0000, v169
	v_lshlrev_b32_e32 v193, 16, v185
	v_and_b32_e32 v185, 0xffff0000, v185
	v_lshlrev_b32_e32 v195, 16, v187
	v_and_b32_e32 v187, 0xffff0000, v187
	v_mov_b32_dpp v189, v183 row_ror:2 row_mask:0xf bank_mask:0xf bound_ctrl:1
	s_waitcnt vmcnt(10)
	v_cndmask_b32_e64 v231, v169, v171, s[0:1]
	s_waitcnt vmcnt(9)
	v_cndmask_b32_e32 v169, v174, v170, vcc
	v_cndmask_b32_e32 v174, v175, v171, vcc
	v_cndmask_b32_e64 v230, v191, v170, s[0:1]
	v_cndmask_b32_e64 v233, v185, v173, s[0:1]
	v_cndmask_b32_e64 v232, v193, v172, s[0:1]
	v_cndmask_b32_e32 v170, v176, v172, vcc
	v_cndmask_b32_e32 v171, v177, v173, vcc
	v_cndmask_b32_e64 v173, v187, v174, s[8:9]
	v_cndmask_b32_e64 v172, v195, v169, s[8:9]
	s_waitcnt vmcnt(7)
	v_pk_fma_f32 v[172:173], v[140:141], v[172:173], v[144:145]
	v_lshlrev_b32_e32 v176, 16, v182
	v_and_b32_e32 v177, 0xffff0000, v182
	s_waitcnt vmcnt(6)
	v_pk_fma_f32 v[172:173], v[136:137], v[230:231], v[172:173]
	v_mov_b32_dpp v189, v183 row_shr:2 row_mask:0xf bank_mask:0xf
	s_waitcnt vmcnt(5)
	v_pk_fma_f32 v[172:173], v[132:133], v[176:177], v[172:173]
	v_lshlrev_b32_e32 v211, 16, v189
	v_and_b32_e32 v189, 0xffff0000, v189
	v_pk_mul_f32 v[176:177], v[172:173], s[30:31] op_sel_hi:[1,0]
	v_cndmask_b32_e64 v171, v189, v171, s[8:9]
	v_cndmask_b32_e64 v170, v211, v170, s[8:9]
	v_med3_f32 v176, v176, s47, v225
	v_med3_f32 v177, v177, s47, v225
	v_pk_fma_f32 v[170:171], v[142:143], v[170:171], v[146:147]
	v_pk_mul_f32 v[230:231], v[176:177], v[176:177]
	v_pk_fma_f32 v[170:171], v[138:139], v[232:233], v[170:171]
	v_pk_fma_f32 v[232:233], v[230:231], s[34:35], v[148:149] op_sel_hi:[1,0,0] neg_lo:[1,0,0] neg_hi:[1,0,0]
	v_pk_mul_f32 v[172:173], v[172:173], 0.5 op_sel_hi:[1,0]
	v_pk_fma_f32 v[232:233], v[230:231], v[232:233], s[38:39] op_sel_hi:[1,1,0]
	v_lshl_add_u64 v[174:175], v[152:153], 0, v[162:163]
	v_pk_fma_f32 v[232:233], v[230:231], v[232:233], s[40:41] op_sel_hi:[1,1,0]
	s_nop 0
	v_pk_fma_f32 v[232:233], v[230:231], v[232:233], s[42:43] op_sel_hi:[1,1,0]
	s_nop 0
	v_pk_fma_f32 v[232:233], v[230:231], v[232:233], s[44:45] op_sel_hi:[1,1,0]
	s_nop 0
	v_pk_fma_f32 v[232:233], v[230:231], v[232:233], s[46:47] op_sel_hi:[1,1,0]
	s_nop 0
	v_pk_fma_f32 v[230:231], v[230:231], v[232:233], s[48:49] op_sel_hi:[1,1,0]
	s_nop 0
	v_pk_mul_f32 v[176:177], v[176:177], v[230:231]
	s_nop 0
	v_pk_fma_f32 v[172:173], v[172:173], v[176:177], v[172:173]
	s_nop 0
	v_mul_f32_e32 v169, v68, v172
	v_mul_f32_e32 v172, v69, v173
	v_mul_f32_e32 v185, v188, v172
	v_lshlrev_b32_e32 v172, 16, v183
	v_and_b32_e32 v173, 0xffff0000, v183
	v_pk_fma_f32 v[170:171], v[134:135], v[172:173], v[170:171]
	v_mul_f32_e32 v169, v188, v169
	v_pk_mul_f32 v[172:173], v[170:171], s[30:31] op_sel_hi:[1,0]
	v_pk_mul_f32 v[170:171], v[170:171], 0.5 op_sel_hi:[1,0]
	v_med3_f32 v172, v172, s47, v225
	v_med3_f32 v173, v173, s47, v225
	v_pk_mul_f32 v[176:177], v[172:173], v[172:173]
	s_nop 0
	v_pk_fma_f32 v[182:183], v[176:177], s[34:35], v[148:149] op_sel_hi:[1,0,0] neg_lo:[1,0,0] neg_hi:[1,0,0]
	s_nop 0
	v_pk_fma_f32 v[182:183], v[176:177], v[182:183], s[38:39] op_sel_hi:[1,1,0]
	s_nop 0
	v_pk_fma_f32 v[182:183], v[176:177], v[182:183], s[40:41] op_sel_hi:[1,1,0]
	s_nop 0
	v_pk_fma_f32 v[182:183], v[176:177], v[182:183], s[42:43] op_sel_hi:[1,1,0]
	s_nop 0
	v_pk_fma_f32 v[182:183], v[176:177], v[182:183], s[44:45] op_sel_hi:[1,1,0]
	s_nop 0
	v_pk_fma_f32 v[182:183], v[176:177], v[182:183], s[46:47] op_sel_hi:[1,1,0]
	s_nop 0
	v_pk_fma_f32 v[176:177], v[176:177], v[182:183], s[48:49] op_sel_hi:[1,1,0]
	s_nop 0
	v_pk_mul_f32 v[172:173], v[172:173], v[176:177]
	s_nop 0
	v_pk_fma_f32 v[170:171], v[170:171], v[172:173], v[170:171]
	s_nop 0
	v_mul_f32_e32 v170, v70, v170
	v_mul_f32_e32 v172, v188, v170
	v_mul_f32_e32 v170, v71, v171
	v_mul_f32_e32 v171, v188, v170
	v_cvt_pk_bf16_f32 v170, v169, v185
	v_cvt_pk_bf16_f32 v171, v172, v171
	s_waitcnt vmcnt(4)
; __device__ __forceinline__ unsigned cvt_pk_bf16(float lo, float hi) { unsigned r; asm volatile("v_cvt_pk_bf16_f32 %0, %1, %2" : "=v"(r) : "v"(lo), "v"(hi)); return r; }
;     static __device__ __forceinline__ void unpk4(const u32x2 w, float (&o)[4]) { o[0] = bf_lo(w.x); o[1] = bf_hi(w.x); o[2] = bf_lo(w.y); o[3] = bf_hi(w.y); }
;     template <int N> static __device__ __forceinline__ u32x2 dpp_prev(const u32x2 pv, const u32x2 cur) { u32x2 r; r.x = dpp_prev1<N>(pv.x, cur.x); r.y = dpp_prev1<N>(pv.y, cur.y); return r; }
;     static __device__ __forceinline__ void finish(const float (&g0)[4], const float (&g1)[4], const float (&g2)[4], const float (&w0)[4], const float (&w1)[4], const float (&w2)[4], const float (&bb)[4],
;                                                   const f32x4 v, float rs, bf16_t* dst) {
;         float h[4];
; #pragma unroll
;         for (int j = 0; j < 4; j += 2) {
;             const f32x2 gc = (f32x2){bb[j] + w0[j] * g2[j] + w1[j] * g1[j] + w2[j] * g0[j], bb[j + 1] + w0[j + 1] * g2[j + 1] + w1[j + 1] * g1[j + 1] + w2[j + 1] * g0[j + 1]};
;             const f32x2 ge = gelu_pk(gc); h[j] = ge.x * v[j] * rs; h[j + 1] = ge.y * v[j + 1] * rs; }
;         u32x2 w; w.x = cvt_pk_bf16(h[0], h[1]); w.y = cvt_pk_bf16(h[2], h[3]);
;         *(u32x2*)dst = w;
;     }
;     __device__ __forceinline__ void operator()(const f32x4 (&acc)[2][2][4][2], const Unit& u, int wr, int wc, int fr, int fq) const {
;     ...
;                 for (int m = mh; m < mh + 2; ++m) { const int row = row0 + m * 16; const float* cx = ctx + (size_t)((row - 32768) >> 3) * 2 * 2816 + col;
;                     c0[m] = *(const f32x4*)cx; c1[m] = *(const f32x4*)(cx + 2816); }
; #pragma unroll
;                 for (int m = mh; m < mh + 2; ++m) { const int row = row0 + m * 16; const u32x2 cur = gq[m];
;                     const u32x2 q1 = dpp_prev<1>(cur, cur), q2 = dpp_prev<2>(cur, cur);
;                     float g0[4], g1[4], g2[4]; unpk4(cur, g0); unpk4(q1, g1); unpk4(q2, g2);
; #pragma unroll
;                     for (int j = 0; j < 4; ++j) { const float x1 = c1[m][j], x0 = c0[m][j];
;                         if (i < 1) g1[j] = x1;
;                         if (i < 2) g2[j] = (i == 1) ? x1 : x0; }
;                     finish(g0, g1, g2, w0, w1, w2, bb, acc[0][bj][m][hv], rs8[0][m], H + (size_t)row * 2816 + col); }
	v_mov_b32_dpp v169, v228 row_ror:1 row_mask:0xf bank_mask:0xf bound_ctrl:1
	global_store_dwordx2 v[174:175], v[170:171], off
	v_mov_b32_dpp v171, v228 row_ror:2 row_mask:0xf bank_mask:0xf bound_ctrl:1
	v_mov_b32_dpp v169, v228 row_shr:1 row_mask:0xf bank_mask:0xf
	v_mov_b32_dpp v170, v229 row_ror:1 row_mask:0xf bank_mask:0xf bound_ctrl:1
	v_mov_b32_dpp v171, v228 row_shr:2 row_mask:0xf bank_mask:0xf
	v_lshlrev_b32_e32 v173, 16, v169
	v_and_b32_e32 v169, 0xffff0000, v169
	v_mov_b32_dpp v170, v229 row_shr:1 row_mask:0xf bank_mask:0xf
	v_mov_b32_dpp v172, v229 row_ror:2 row_mask:0xf bank_mask:0xf bound_ctrl:1
	v_lshlrev_b32_e32 v176, 16, v171
	v_and_b32_e32 v177, 0xffff0000, v171
	s_waitcnt vmcnt(1)
	v_cndmask_b32_e64 v171, v169, v213, s[0:1]
	v_cndmask_b32_e32 v169, v178, v212, vcc
	v_cndmask_b32_e32 v178, v179, v213, vcc
	v_mov_b32_dpp v172, v229 row_shr:2 row_mask:0xf bank_mask:0xf
	v_lshlrev_b32_e32 v174, 16, v170
	v_and_b32_e32 v175, 0xffff0000, v170
	v_cndmask_b32_e64 v177, v177, v178, s[8:9]
	v_cndmask_b32_e64 v176, v176, v169, s[8:9]
	v_lshlrev_b32_e32 v182, 16, v172
	v_and_b32_e32 v183, 0xffff0000, v172
	v_cndmask_b32_e64 v170, v173, v212, s[0:1]
	v_cndmask_b32_e64 v173, v175, v215, s[0:1]
	v_cndmask_b32_e64 v172, v174, v214, s[0:1]
	v_cndmask_b32_e32 v174, v180, v214, vcc
	v_cndmask_b32_e32 v175, v181, v215, vcc
	v_pk_fma_f32 v[176:177], v[140:141], v[176:177], v[144:145]
	v_cndmask_b32_e64 v175, v183, v175, s[8:9]
	v_cndmask_b32_e64 v174, v182, v174, s[8:9]
	v_lshlrev_b32_e32 v180, 16, v228
	v_and_b32_e32 v181, 0xffff0000, v228
	v_pk_fma_f32 v[170:171], v[136:137], v[170:171], v[176:177]
	v_pk_fma_f32 v[174:175], v[142:143], v[174:175], v[146:147]
	v_pk_fma_f32 v[170:171], v[132:133], v[180:181], v[170:171]
	v_pk_fma_f32 v[172:173], v[138:139], v[172:173], v[174:175]
	v_pk_mul_f32 v[174:175], v[170:171], s[30:31] op_sel_hi:[1,0]
	v_pk_mul_f32 v[170:171], v[170:171], 0.5 op_sel_hi:[1,0]
	v_med3_f32 v174, v174, s47, v225
	v_med3_f32 v175, v175, s47, v225
	v_pk_mul_f32 v[176:177], v[174:175], v[174:175]
	v_lshl_add_u64 v[178:179], v[154:155], 0, v[162:163]
	v_pk_fma_f32 v[180:181], v[176:177], s[34:35], v[148:149] op_sel_hi:[1,0,0] neg_lo:[1,0,0] neg_hi:[1,0,0]
	v_mov_b32_dpp v185, v165 row_ror:2 row_mask:0xf bank_mask:0xf bound_ctrl:1
	v_pk_fma_f32 v[180:181], v[176:177], v[180:181], s[38:39] op_sel_hi:[1,1,0]
	s_nop 0
	v_pk_fma_f32 v[180:181], v[176:177], v[180:181], s[40:41] op_sel_hi:[1,1,0]
	v_mov_b32_dpp v185, v165 row_shr:2 row_mask:0xf bank_mask:0xf
	v_pk_fma_f32 v[180:181], v[176:177], v[180:181], s[42:43] op_sel_hi:[1,1,0]
	v_lshlrev_b32_e32 v211, 16, v185
	v_pk_fma_f32 v[180:181], v[176:177], v[180:181], s[44:45] op_sel_hi:[1,1,0]
	v_and_b32_e32 v185, 0xffff0000, v185
	v_pk_fma_f32 v[180:181], v[176:177], v[180:181], s[46:47] op_sel_hi:[1,1,0]
	s_nop 0
	v_pk_fma_f32 v[176:177], v[176:177], v[180:181], s[48:49] op_sel_hi:[1,1,0]
	s_nop 0
	v_pk_mul_f32 v[174:175], v[174:175], v[176:177]
	s_nop 0
	v_pk_fma_f32 v[170:171], v[170:171], v[174:175], v[170:171]
	s_nop 0
	v_mul_f32_e32 v169, v56, v170
	v_mul_f32_e32 v170, v57, v171
	v_mul_f32_e32 v180, v186, v170
	v_lshlrev_b32_e32 v170, 16, v229
	v_and_b32_e32 v171, 0xffff0000, v229
	v_pk_fma_f32 v[170:171], v[134:135], v[170:171], v[172:173]
	v_mul_f32_e32 v169, v186, v169
	v_pk_mul_f32 v[172:173], v[170:171], s[30:31] op_sel_hi:[1,0]
	v_pk_mul_f32 v[170:171], v[170:171], 0.5 op_sel_hi:[1,0]
	v_med3_f32 v172, v172, s47, v225
	v_med3_f32 v173, v173, s47, v225
	v_pk_mul_f32 v[174:175], v[172:173], v[172:173]
	s_nop 0
	v_pk_fma_f32 v[176:177], v[174:175], s[34:35], v[148:149] op_sel_hi:[1,0,0] neg_lo:[1,0,0] neg_hi:[1,0,0]
	s_nop 0
	v_pk_fma_f32 v[176:177], v[174:175], v[176:177], s[38:39] op_sel_hi:[1,1,0]
	s_nop 0
	v_pk_fma_f32 v[176:177], v[174:175], v[176:177], s[40:41] op_sel_hi:[1,1,0]
	s_nop 0
	v_pk_fma_f32 v[176:177], v[174:175], v[176:177], s[42:43] op_sel_hi:[1,1,0]
	s_nop 0
	v_pk_fma_f32 v[176:177], v[174:175], v[176:177], s[44:45] op_sel_hi:[1,1,0]
	s_nop 0
	v_pk_fma_f32 v[176:177], v[174:175], v[176:177], s[46:47] op_sel_hi:[1,1,0]
	s_nop 0
	v_pk_fma_f32 v[174:175], v[174:175], v[176:177], s[48:49] op_sel_hi:[1,1,0]
	s_nop 0
	v_pk_mul_f32 v[172:173], v[172:173], v[174:175]
	v_mad_i64_i32 v[174:175], s[10:11], v166, s45, v[226:227]
	v_pk_fma_f32 v[170:171], v[170:171], v[172:173], v[170:171]
	s_nop 0
	v_mul_f32_e32 v170, v58, v170
	v_mul_f32_e32 v172, v186, v170
	v_mul_f32_e32 v170, v59, v171
	v_mul_f32_e32 v171, v186, v170
	v_cvt_pk_bf16_f32 v170, v169, v180
	v_cvt_pk_bf16_f32 v171, v172, v171
	global_store_dwordx2 v[178:179], v[170:171], off
	v_add_co_u32_e64 v170, s[10:11], s41, v174
	v_mov_b32_dpp v169, v164 row_ror:1 row_mask:0xf bank_mask:0xf bound_ctrl:1
	s_nop 0
	v_addc_co_u32_e64 v171, s[10:11], 0, v175, s[10:11]
	global_load_dwordx4 v[170:173], v[170:171], off offset:3072
	s_nop 0
	global_load_dwordx4 v[174:177], v[174:175], off
	v_mad_i64_i32 v[178:179], s[10:11], v167, s45, v[226:227]
	v_add_co_u32_e64 v182, s[10:11], s41, v178
	v_mov_b32_dpp v169, v164 row_shr:1 row_mask:0xf bank_mask:0xf
	s_nop 0
	v_addc_co_u32_e64 v183, s[10:11], 0, v179, s[10:11]
	global_load_dwordx4 v[178:181], v[178:179], off
	s_nop 0
	global_load_dwordx4 v[212:215], v[182:183], off offset:3072
	v_mov_b32_dpp v182, v165 row_ror:1 row_mask:0xf bank_mask:0xf bound_ctrl:1
	v_mov_b32_dpp v183, v164 row_ror:2 row_mask:0xf bank_mask:0xf bound_ctrl:1
	v_lshlrev_b32_e32 v187, 16, v169
	v_mov_b32_dpp v182, v165 row_shr:1 row_mask:0xf bank_mask:0xf
	v_mov_b32_dpp v183, v164 row_shr:2 row_mask:0xf bank_mask:0xf
	v_and_b32_e32 v169, 0xffff0000, v169
	v_lshlrev_b32_e32 v189, 16, v182
	v_and_b32_e32 v191, 0xffff0000, v182
	v_lshlrev_b32_e32 v193, 16, v183
	v_and_b32_e32 v195, 0xffff0000, v183
	s_waitcnt vmcnt(3)
; __device__ __forceinline__ unsigned cvt_pk_bf16(float lo, float hi) { unsigned r; asm volatile("v_cvt_pk_bf16_f32 %0, %1, %2" : "=v"(r) : "v"(lo), "v"(hi)); return r; }
;     static __device__ __forceinline__ void unpk4(const u32x2 w, float (&o)[4]) { o[0] = bf_lo(w.x); o[1] = bf_hi(w.x); o[2] = bf_lo(w.y); o[3] = bf_hi(w.y); }
;     template <int N> static __device__ __forceinline__ u32x2 dpp_prev(const u32x2 pv, const u32x2 cur) { u32x2 r; r.x = dpp_prev1<N>(pv.x, cur.x); r.y = dpp_prev1<N>(pv.y, cur.y); return r; }
;     static __device__ __forceinline__ void finish(const float (&g0)[4], const float (&g1)[4], const float (&g2)[4], const float (&w0)[4], const float (&w1)[4], const float (&w2)[4], const float (&bb)[4],
;                                                   const f32x4 v, float rs, bf16_t* dst) {
;         float h[4];
; #pragma unroll
;         for (int j = 0; j < 4; j += 2) {
;             const f32x2 gc = (f32x2){bb[j] + w0[j] * g2[j] + w1[j] * g1[j] + w2[j] * g0[j], bb[j + 1] + w0[j + 1] * g2[j + 1] + w1[j + 1] * g1[j + 1] + w2[j + 1] * g0[j + 1]};
;             const f32x2 ge = gelu_pk(gc); h[j] = ge.x * v[j] * rs; h[j + 1] = ge.y * v[j + 1] * rs; }
;         u32x2 w; w.x = cvt_pk_bf16(h[0], h[1]); w.y = cvt_pk_bf16(h[2], h[3]);
;         *(u32x2*)dst = w;
;     }
;     __device__ __forceinline__ void operator()(const f32x4 (&acc)[2][2][4][2], const Unit& u, int wr, int wc, int fr, int fq) const {
;     ...
;                 for (int m = mh; m < mh + 2; ++m) { const int row = row0 + m * 16; const u32x2 cur = gq[m];
;                     const u32x2 q1 = dpp_prev<1>(cur, cur), q2 = dpp_prev<2>(cur, cur);
;                     float g0[4], g1[4], g2[4]; unpk4(cur, g0); unpk4(q1, g1); unpk4(q2, g2);
; #pragma unroll
;                     for (int j = 0; j < 4; ++j) { const float x1 = c1[m][j], x0 = c0[m][j];
;                         if (i < 1) g1[j] = x1;
;                         if (i < 2) g2[j] = (i == 1) ? x1 : x0; }
;                     finish(g0, g1, g2, w0, w1, w2, bb, acc[0][bj][m][hv], rs8[0][m], H + (size_t)row * 2816 + col); }
	v_cndmask_b32_e64 v183, v169, v171, s[0:1]
	s_waitcnt vmcnt(2)
	v_cndmask_b32_e32 v169, v174, v170, vcc
	v_cndmask_b32_e32 v174, v175, v171, vcc
	v_cndmask_b32_e64 v182, v187, v170, s[0:1]
	v_cndmask_b32_e64 v227, v191, v173, s[0:1]
	v_cndmask_b32_e64 v226, v189, v172, s[0:1]
	v_cndmask_b32_e32 v170, v176, v172, vcc
	v_cndmask_b32_e32 v171, v177, v173, vcc
	v_cndmask_b32_e64 v173, v195, v174, s[8:9]
	v_cndmask_b32_e64 v172, v193, v169, s[8:9]
	v_pk_fma_f32 v[172:173], v[140:141], v[172:173], v[144:145]
	v_lshlrev_b32_e32 v176, 16, v164
	v_and_b32_e32 v177, 0xffff0000, v164
	v_pk_fma_f32 v[172:173], v[136:137], v[182:183], v[172:173]
	v_cndmask_b32_e64 v171, v185, v171, s[8:9]
	v_pk_fma_f32 v[172:173], v[132:133], v[176:177], v[172:173]
	v_cndmask_b32_e64 v170, v211, v170, s[8:9]
	v_pk_mul_f32 v[176:177], v[172:173], s[30:31] op_sel_hi:[1,0]
	v_pk_fma_f32 v[170:171], v[142:143], v[170:171], v[146:147]
	v_med3_f32 v176, v176, s47, v225
	v_med3_f32 v177, v177, s47, v225
	v_pk_mul_f32 v[182:183], v[176:177], v[176:177]
	v_pk_fma_f32 v[170:171], v[138:139], v[226:227], v[170:171]
	v_pk_fma_f32 v[226:227], v[182:183], s[34:35], v[148:149] op_sel_hi:[1,0,0] neg_lo:[1,0,0] neg_hi:[1,0,0]
	v_pk_mul_f32 v[172:173], v[172:173], 0.5 op_sel_hi:[1,0]
	v_pk_fma_f32 v[226:227], v[182:183], v[226:227], s[38:39] op_sel_hi:[1,1,0]
	v_lshl_add_u64 v[174:175], v[156:157], 0, v[162:163]
	v_pk_fma_f32 v[226:227], v[182:183], v[226:227], s[40:41] op_sel_hi:[1,1,0]
	v_lshl_add_u64 v[162:163], v[158:159], 0, v[162:163]
	v_pk_fma_f32 v[226:227], v[182:183], v[226:227], s[42:43] op_sel_hi:[1,1,0]
	s_nop 0
	v_pk_fma_f32 v[226:227], v[182:183], v[226:227], s[44:45] op_sel_hi:[1,1,0]
	s_nop 0
	v_pk_fma_f32 v[226:227], v[182:183], v[226:227], s[46:47] op_sel_hi:[1,1,0]
	s_nop 0
	v_pk_fma_f32 v[182:183], v[182:183], v[226:227], s[48:49] op_sel_hi:[1,1,0]
	s_nop 0
	v_pk_mul_f32 v[176:177], v[176:177], v[182:183]
	s_nop 0
	v_pk_fma_f32 v[172:173], v[172:173], v[176:177], v[172:173]
	s_nop 0
	v_mul_f32_e32 v164, v48, v172
	v_mul_f32_e32 v169, v184, v164
	v_mul_f32_e32 v164, v49, v173
	v_mul_f32_e32 v182, v184, v164
	v_lshlrev_b32_e32 v164, 16, v165
	v_and_b32_e32 v165, 0xffff0000, v165
	v_pk_fma_f32 v[164:165], v[134:135], v[164:165], v[170:171]
	s_nop 0
	v_pk_mul_f32 v[170:171], v[164:165], s[30:31] op_sel_hi:[1,0]
	v_pk_mul_f32 v[164:165], v[164:165], 0.5 op_sel_hi:[1,0]
	v_med3_f32 v170, v170, s47, v225
	v_med3_f32 v171, v171, s47, v225
	v_pk_mul_f32 v[172:173], v[170:171], v[170:171]
	s_nop 0
	v_pk_fma_f32 v[176:177], v[172:173], s[34:35], v[148:149] op_sel_hi:[1,0,0] neg_lo:[1,0,0] neg_hi:[1,0,0]
	s_nop 0
	v_pk_fma_f32 v[176:177], v[172:173], v[176:177], s[38:39] op_sel_hi:[1,1,0]
	s_nop 0
	v_pk_fma_f32 v[176:177], v[172:173], v[176:177], s[40:41] op_sel_hi:[1,1,0]
	s_nop 0
	v_pk_fma_f32 v[176:177], v[172:173], v[176:177], s[42:43] op_sel_hi:[1,1,0]
	s_nop 0
	v_pk_fma_f32 v[176:177], v[172:173], v[176:177], s[44:45] op_sel_hi:[1,1,0]
	s_nop 0
	v_pk_fma_f32 v[176:177], v[172:173], v[176:177], s[46:47] op_sel_hi:[1,1,0]
	s_nop 0
	v_pk_fma_f32 v[172:173], v[172:173], v[176:177], s[48:49] op_sel_hi:[1,1,0]
	s_waitcnt vmcnt(0)
	v_cndmask_b32_e32 v177, v178, v212, vcc
	v_pk_mul_f32 v[170:171], v[170:171], v[172:173]
	v_cndmask_b32_e32 v178, v179, v213, vcc
	v_pk_fma_f32 v[164:165], v[164:165], v[170:171], v[164:165]
	s_nop 0
	v_mul_f32_e32 v164, v50, v164
	v_mul_f32_e32 v170, v184, v164
	v_mul_f32_e32 v164, v51, v165
	v_mul_f32_e32 v165, v184, v164
	v_cvt_pk_bf16_f32 v164, v169, v182
	v_cvt_pk_bf16_f32 v165, v170, v165
	global_store_dwordx2 v[174:175], v[164:165], off
	v_mov_b32_dpp v169, v160 row_ror:2 row_mask:0xf bank_mask:0xf bound_ctrl:1
	v_mov_b32_dpp v165, v161 row_ror:1 row_mask:0xf bank_mask:0xf bound_ctrl:1
	v_mov_b32_dpp v170, v161 row_ror:2 row_mask:0xf bank_mask:0xf bound_ctrl:1
	v_mov_b32_dpp v164, v160 row_ror:1 row_mask:0xf bank_mask:0xf bound_ctrl:1
	v_mov_b32_dpp v165, v161 row_shr:1 row_mask:0xf bank_mask:0xf
	v_mov_b32_dpp v169, v160 row_shr:2 row_mask:0xf bank_mask:0xf
	v_mov_b32_dpp v170, v161 row_shr:2 row_mask:0xf bank_mask:0xf
	v_lshlrev_b32_e32 v172, 16, v165
	v_mov_b32_dpp v164, v160 row_shr:1 row_mask:0xf bank_mask:0xf
	v_lshlrev_b32_e32 v174, 16, v169
	v_and_b32_e32 v169, 0xffff0000, v169
	v_lshlrev_b32_e32 v175, 16, v170
	v_and_b32_e32 v176, 0xffff0000, v170
	v_cndmask_b32_e64 v170, v172, v214, s[0:1]
	v_cndmask_b32_e32 v172, v180, v214, vcc
	v_lshlrev_b32_e32 v171, 16, v164
	v_and_b32_e32 v164, 0xffff0000, v164
	v_and_b32_e32 v173, 0xffff0000, v165
	v_cndmask_b32_e64 v172, v175, v172, s[8:9]
	v_cndmask_b32_e64 v175, v169, v178, s[8:9]
	v_cndmask_b32_e64 v174, v174, v177, s[8:9]
	v_cndmask_b32_e64 v165, v164, v213, s[0:1]
	v_cndmask_b32_e64 v164, v171, v212, s[0:1]
	v_cndmask_b32_e64 v171, v173, v215, s[0:1]
	v_cndmask_b32_e32 v173, v181, v215, vcc
	v_pk_fma_f32 v[140:141], v[140:141], v[174:175], v[144:145]
	v_cndmask_b32_e64 v173, v176, v173, s[8:9]
	v_lshlrev_b32_e32 v176, 16, v160
	v_and_b32_e32 v177, 0xffff0000, v160
	v_pk_fma_f32 v[136:137], v[136:137], v[164:165], v[140:141]
	v_pk_fma_f32 v[142:143], v[142:143], v[172:173], v[146:147]
	v_pk_fma_f32 v[132:133], v[132:133], v[176:177], v[136:137]
	v_pk_fma_f32 v[138:139], v[138:139], v[170:171], v[142:143]
	v_pk_mul_f32 v[136:137], v[132:133], s[30:31] op_sel_hi:[1,0]
	v_pk_mul_f32 v[132:133], v[132:133], 0.5 op_sel_hi:[1,0]
	v_med3_f32 v136, v136, s47, v225
	v_med3_f32 v137, v137, s47, v225
	v_pk_mul_f32 v[140:141], v[136:137], v[136:137]
	s_nop 0
	v_pk_fma_f32 v[142:143], v[140:141], s[34:35], v[148:149] op_sel_hi:[1,0,0] neg_lo:[1,0,0] neg_hi:[1,0,0]
	s_nop 0
;     static __device__ __forceinline__ void finish(const float (&g0)[4], const float (&g1)[4], const float (&g2)[4], const float (&w0)[4], const float (&w1)[4], const float (&w2)[4], const float (&bb)[4],
;                                                   const f32x4 v, float rs, bf16_t* dst) {
;         float h[4];
; #pragma unroll
;         for (int j = 0; j < 4; j += 2) {
;             const f32x2 gc = (f32x2){bb[j] + w0[j] * g2[j] + w1[j] * g1[j] + w2[j] * g0[j], bb[j + 1] + w0[j + 1] * g2[j + 1] + w1[j + 1] * g1[j + 1] + w2[j + 1] * g0[j + 1]};
;     __device__ __forceinline__ void operator()(const f32x4 (&acc)[2][2][4][2], const Unit& u, int wr, int wc, int fr, int fq) const {
;     ...
;         for (int bj = 0; bj < 2; ++bj)
; #pragma unroll
;           for (int hv = 0; hv < 2; ++hv) {
;             const int col = u.pn * BM + bj * HALF + wc * 32 + 8 * fq + 4 * hv;
;             float w0[4], w1[4], w2[4], bb[4];
;             ld4f(cw + col, w0); ld4f(cw + 2816 + col, w1); ld4f(cw + 2 * 2816 + col, w2); ld4f(cb + col, bb);
;             {
;                 const int i = fr & 7;
;                 u32x2 gq[4];
; #pragma unroll
;                 for (int m = 0; m < 4; ++m) { const int row = row0 + m * 16; gq[m] = *(const u32x2*)(G + (size_t)row * 2816 + col); }
; #pragma unroll
;                 for (int mh = 0; mh < 4; mh += 2) {
;                 f32x4 c0[4], c1[4];
; #pragma unroll
;                 for (int m = mh; m < mh + 2; ++m) { const int row = row0 + m * 16; const float* cx = ctx + (size_t)((row - 32768) >> 3) * 2 * 2816 + col;
;                     c0[m] = *(const f32x4*)cx; c1[m] = *(const f32x4*)(cx + 2816); }
; #pragma unroll
;                 for (int m = mh; m < mh + 2; ++m) { const int row = row0 + m * 16; const u32x2 cur = gq[m];
;                     const u32x2 q1 = dpp_prev<1>(cur, cur), q2 = dpp_prev<2>(cur, cur);
;                     float g0[4], g1[4], g2[4]; unpk4(cur, g0); unpk4(q1, g1); unpk4(q2, g2);
; #pragma unroll
;                     for (int j = 0; j < 4; ++j) { const float x1 = c1[m][j], x0 = c0[m][j];
;                         if (i < 1) g1[j] = x1;
;                         if (i < 2) g2[j] = (i == 1) ? x1 : x0; }
;                     finish(g0, g1, g2, w0, w1, w2, bb, acc[0][bj][m][hv], rs8[0][m], H + (size_t)row * 2816 + col); }
	v_pk_fma_f32 v[142:143], v[140:141], v[142:143], s[38:39] op_sel_hi:[1,1,0]
	s_nop 0
	v_pk_fma_f32 v[142:143], v[140:141], v[142:143], s[40:41] op_sel_hi:[1,1,0]
	s_nop 0
	v_pk_fma_f32 v[142:143], v[140:141], v[142:143], s[42:43] op_sel_hi:[1,1,0]
	s_nop 0
	v_pk_fma_f32 v[142:143], v[140:141], v[142:143], s[44:45] op_sel_hi:[1,1,0]
	s_nop 0
	v_pk_fma_f32 v[142:143], v[140:141], v[142:143], s[46:47] op_sel_hi:[1,1,0]
	s_nop 0
	v_pk_fma_f32 v[140:141], v[140:141], v[142:143], s[48:49] op_sel_hi:[1,1,0]
	s_nop 0
	v_pk_mul_f32 v[136:137], v[136:137], v[140:141]
	s_nop 0
	v_pk_fma_f32 v[132:133], v[132:133], v[136:137], v[132:133]
	s_nop 0
	v_mul_f32_e32 v132, v40, v132
	v_mul_f32_e32 v140, v2, v132
	v_mul_f32_e32 v132, v41, v133
	v_mul_f32_e32 v141, v2, v132
	v_lshlrev_b32_e32 v132, 16, v161
	v_and_b32_e32 v133, 0xffff0000, v161
	v_pk_fma_f32 v[132:133], v[134:135], v[132:133], v[138:139]
	s_nop 0
	v_pk_mul_f32 v[134:135], v[132:133], s[30:31] op_sel_hi:[1,0]
	v_pk_mul_f32 v[132:133], v[132:133], 0.5 op_sel_hi:[1,0]
	v_med3_f32 v134, v134, s47, v225
	v_med3_f32 v135, v135, s47, v225
	v_pk_mul_f32 v[136:137], v[134:135], v[134:135]
	s_nop 0
	v_pk_fma_f32 v[138:139], v[136:137], s[34:35], v[148:149] op_sel_hi:[1,0,0] neg_lo:[1,0,0] neg_hi:[1,0,0]
	s_nop 0
	v_pk_fma_f32 v[138:139], v[136:137], v[138:139], s[38:39] op_sel_hi:[1,1,0]
	s_nop 0
	v_pk_fma_f32 v[138:139], v[136:137], v[138:139], s[40:41] op_sel_hi:[1,1,0]
	s_nop 0
	v_pk_fma_f32 v[138:139], v[136:137], v[138:139], s[42:43] op_sel_hi:[1,1,0]
	s_nop 0
	v_pk_fma_f32 v[138:139], v[136:137], v[138:139], s[44:45] op_sel_hi:[1,1,0]
	s_nop 0
	v_pk_fma_f32 v[138:139], v[136:137], v[138:139], s[46:47] op_sel_hi:[1,1,0]
	s_nop 0
	v_pk_fma_f32 v[136:137], v[136:137], v[138:139], s[48:49] op_sel_hi:[1,1,0]
	s_nop 0
	v_pk_mul_f32 v[134:135], v[134:135], v[136:137]
	s_nop 0
	v_pk_fma_f32 v[132:133], v[132:133], v[134:135], v[132:133]
	s_nop 0
	v_mul_f32_e32 v132, v42, v132
	v_mul_f32_e32 v134, v2, v132
	v_mul_f32_e32 v132, v43, v133
	v_mul_f32_e32 v133, v2, v132
	v_cvt_pk_bf16_f32 v132, v140, v141
	v_cvt_pk_bf16_f32 v133, v134, v133
	global_store_dwordx2 v[162:163], v[132:133], off
	v_add_u32_e32 v132, 0x84, v150
	v_ashrrev_i32_e32 v133, 31, v132
	v_lshlrev_b64 v[160:161], 1, v[132:133]
	v_lshl_add_u64 v[162:163], s[68:69], 0, v[160:161]
	v_lshlrev_b64 v[132:133], 2, v[132:133]
	v_mad_i64_i32 v[134:135], s[10:11], v210, s91, v[162:163]
	v_lshl_add_u64 v[182:183], s[82:83], 0, v[132:133]
	global_load_dwordx2 v[164:165], v[134:135], off
	v_mad_i64_i32 v[134:135], s[10:11], v151, s45, v[182:183]
	v_add_co_u32_e64 v136, s[10:11], s41, v134
	v_lshl_add_u64 v[152:153], v[152:153], 0, v[160:161]
	s_nop 0
	v_addc_co_u32_e64 v137, s[10:11], 0, v135, s[10:11]
	global_load_dwordx4 v[170:173], v[136:137], off offset:3072
	global_load_dwordx4 v[174:177], v[134:135], off
	v_lshl_add_u64 v[134:135], s[66:67], 0, v[132:133]
	global_load_dwordx4 v[140:143], v[134:135], off
	v_lshl_add_u64 v[134:135], s[88:89], 0, v[132:133]
	global_load_dwordx4 v[144:147], v[134:135], off
	v_lshl_add_u64 v[134:135], s[52:53], 0, v[132:133]
	global_load_dwordx4 v[136:139], v[134:135], off
	v_lshl_add_u64 v[132:133], s[54:55], 0, v[132:133]
	global_load_dwordx4 v[132:135], v[132:133], off
	v_mad_i64_i32 v[150:151], s[10:11], v194, s91, v[162:163]
	v_mad_i64_i32 v[178:179], s[10:11], v192, s91, v[162:163]
	v_mad_i64_i32 v[180:181], s[10:11], v190, s91, v[162:163]
	v_mad_i64_i32 v[168:169], s[10:11], v168, s45, v[182:183]
	v_add_co_u32_e64 v212, s[10:11], s41, v168
	global_load_dwordx2 v[226:227], v[150:151], off
	global_load_dwordx2 v[162:163], v[178:179], off
	s_nop 0
	global_load_dwordx2 v[150:151], v[180:181], off
	v_addc_co_u32_e64 v213, s[10:11], 0, v169, s[10:11]
	global_load_dwordx4 v[178:181], v[168:169], off
	s_nop 0
	global_load_dwordx4 v[212:215], v[212:213], off offset:3072
	v_lshl_add_u64 v[154:155], v[154:155], 0, v[160:161]
	v_lshl_add_u64 v[156:157], v[156:157], 0, v[160:161]
	v_lshl_add_u64 v[158:159], v[158:159], 0, v[160:161]
	s_mov_b64 s[54:55], s[86:87]
	s_waitcnt vmcnt(11)
	v_mov_b32_dpp v168, v164 row_ror:1 row_mask:0xf bank_mask:0xf bound_ctrl:1
	v_mov_b32_dpp v169, v165 row_ror:1 row_mask:0xf bank_mask:0xf bound_ctrl:1
	v_mov_b32_dpp v185, v164 row_ror:2 row_mask:0xf bank_mask:0xf bound_ctrl:1
	v_mov_b32_dpp v168, v164 row_shr:1 row_mask:0xf bank_mask:0xf
	v_mov_b32_dpp v169, v165 row_shr:1 row_mask:0xf bank_mask:0xf
	v_mov_b32_dpp v185, v164 row_shr:2 row_mask:0xf bank_mask:0xf
	v_lshlrev_b32_e32 v189, 16, v168
	v_and_b32_e32 v168, 0xffff0000, v168
	v_lshlrev_b32_e32 v191, 16, v169
	v_and_b32_e32 v193, 0xffff0000, v169
	v_lshlrev_b32_e32 v195, 16, v185
	v_and_b32_e32 v185, 0xffff0000, v185
	s_waitcnt vmcnt(9)
	v_cndmask_b32_e32 v174, v174, v170, vcc
	v_cndmask_b32_e32 v175, v175, v171, vcc
	v_cndmask_b32_e64 v169, v168, v171, s[0:1]
	v_cndmask_b32_e64 v168, v189, v170, s[0:1]
	v_cndmask_b32_e64 v229, v193, v173, s[0:1]
	v_cndmask_b32_e64 v228, v191, v172, s[0:1]
	v_cndmask_b32_e32 v170, v176, v172, vcc
	v_cndmask_b32_e32 v171, v177, v173, vcc
	v_cndmask_b32_e64 v173, v185, v175, s[8:9]
	v_cndmask_b32_e64 v172, v195, v174, s[8:9]
	s_waitcnt vmcnt(7)
	v_pk_fma_f32 v[172:173], v[140:141], v[172:173], v[144:145]
	v_lshlrev_b32_e32 v174, 16, v164
	v_and_b32_e32 v175, 0xffff0000, v164
	s_waitcnt vmcnt(6)
	v_pk_fma_f32 v[168:169], v[136:137], v[168:169], v[172:173]
	v_mov_b32_dpp v187, v165 row_ror:2 row_mask:0xf bank_mask:0xf bound_ctrl:1
	s_waitcnt vmcnt(5)
	v_pk_fma_f32 v[168:169], v[132:133], v[174:175], v[168:169]
	s_waitcnt vmcnt(2)
; __device__ __forceinline__ unsigned cvt_pk_bf16(float lo, float hi) { unsigned r; asm volatile("v_cvt_pk_bf16_f32 %0, %1, %2" : "=v"(r) : "v"(lo), "v"(hi)); return r; }
;     static __device__ __forceinline__ void unpk4(const u32x2 w, float (&o)[4]) { o[0] = bf_lo(w.x); o[1] = bf_hi(w.x); o[2] = bf_lo(w.y); o[3] = bf_hi(w.y); }
;     template <int N> static __device__ __forceinline__ u32x2 dpp_prev(const u32x2 pv, const u32x2 cur) { u32x2 r; r.x = dpp_prev1<N>(pv.x, cur.x); r.y = dpp_prev1<N>(pv.y, cur.y); return r; }
;     static __device__ __forceinline__ void finish(const float (&g0)[4], const float (&g1)[4], const float (&g2)[4], const float (&w0)[4], const float (&w1)[4], const float (&w2)[4], const float (&bb)[4],
;                                                   const f32x4 v, float rs, bf16_t* dst) {
;         float h[4];
; #pragma unroll
;         for (int j = 0; j < 4; j += 2) {
;             const f32x2 gc = (f32x2){bb[j] + w0[j] * g2[j] + w1[j] * g1[j] + w2[j] * g0[j], bb[j + 1] + w0[j + 1] * g2[j + 1] + w1[j + 1] * g1[j + 1] + w2[j + 1] * g0[j + 1]};
;             const f32x2 ge = gelu_pk(gc); h[j] = ge.x * v[j] * rs; h[j + 1] = ge.y * v[j + 1] * rs; }
;         u32x2 w; w.x = cvt_pk_bf16(h[0], h[1]); w.y = cvt_pk_bf16(h[2], h[3]);
;         *(u32x2*)dst = w;
;     }
;     __device__ __forceinline__ void operator()(const f32x4 (&acc)[2][2][4][2], const Unit& u, int wr, int wc, int fr, int fq) const {
;     ...
;                 for (int m = mh; m < mh + 2; ++m) { const int row = row0 + m * 16; const u32x2 cur = gq[m];
;                     const u32x2 q1 = dpp_prev<1>(cur, cur), q2 = dpp_prev<2>(cur, cur);
;                     float g0[4], g1[4], g2[4]; unpk4(cur, g0); unpk4(q1, g1); unpk4(q2, g2);
; #pragma unroll
;                     for (int j = 0; j < 4; ++j) { const float x1 = c1[m][j], x0 = c0[m][j];
;                         if (i < 1) g1[j] = x1;
;                         if (i < 2) g2[j] = (i == 1) ? x1 : x0; }
;                     finish(g0, g1, g2, w0, w1, w2, bb, acc[0][bj][m][hv], rs8[0][m], H + (size_t)row * 2816 + col); }
	v_lshlrev_b32_e32 v160, 16, v150
	v_pk_mul_f32 v[172:173], v[168:169], s[30:31] op_sel_hi:[1,0]
	v_mov_b32_dpp v187, v165 row_shr:2 row_mask:0xf bank_mask:0xf
	v_med3_f32 v172, v172, s47, v225
	v_med3_f32 v173, v173, s47, v225
	v_pk_mul_f32 v[174:175], v[172:173], v[172:173]
	v_pk_mul_f32 v[168:169], v[168:169], 0.5 op_sel_hi:[1,0]
	v_pk_fma_f32 v[176:177], v[174:175], s[34:35], v[148:149] op_sel_hi:[1,0,0] neg_lo:[1,0,0] neg_hi:[1,0,0]
	v_lshlrev_b32_e32 v211, 16, v187
	v_pk_fma_f32 v[176:177], v[174:175], v[176:177], s[38:39] op_sel_hi:[1,1,0]
	v_and_b32_e32 v187, 0xffff0000, v187
	v_pk_fma_f32 v[176:177], v[174:175], v[176:177], s[40:41] op_sel_hi:[1,1,0]
	v_cndmask_b32_e64 v171, v187, v171, s[8:9]
	v_pk_fma_f32 v[176:177], v[174:175], v[176:177], s[42:43] op_sel_hi:[1,1,0]
	v_cndmask_b32_e64 v170, v211, v170, s[8:9]
	v_pk_fma_f32 v[176:177], v[174:175], v[176:177], s[44:45] op_sel_hi:[1,1,0]
	v_pk_fma_f32 v[170:171], v[142:143], v[170:171], v[146:147]
	v_pk_fma_f32 v[176:177], v[174:175], v[176:177], s[46:47] op_sel_hi:[1,1,0]
	v_pk_fma_f32 v[170:171], v[138:139], v[228:229], v[170:171]
	v_pk_fma_f32 v[174:175], v[174:175], v[176:177], s[48:49] op_sel_hi:[1,1,0]
	v_mov_b32_dpp v176, v162 row_ror:1 row_mask:0xf bank_mask:0xf bound_ctrl:1
	v_pk_mul_f32 v[172:173], v[172:173], v[174:175]
	v_mov_b32_dpp v177, v163 row_ror:1 row_mask:0xf bank_mask:0xf bound_ctrl:1
	v_pk_fma_f32 v[168:169], v[168:169], v[172:173], v[168:169]
	v_mov_b32_dpp v176, v162 row_shr:1 row_mask:0xf bank_mask:0xf
	v_mul_f32_e32 v164, v60, v168
	v_mul_f32_e32 v174, v188, v164
	v_mul_f32_e32 v164, v61, v169
	v_mul_f32_e32 v175, v188, v164
	v_lshlrev_b32_e32 v164, 16, v165
	v_and_b32_e32 v165, 0xffff0000, v165
	v_pk_fma_f32 v[164:165], v[134:135], v[164:165], v[170:171]
	v_mov_b32_dpp v177, v163 row_shr:1 row_mask:0xf bank_mask:0xf
	v_pk_mul_f32 v[168:169], v[164:165], s[30:31] op_sel_hi:[1,0]
	v_pk_mul_f32 v[164:165], v[164:165], 0.5 op_sel_hi:[1,0]
	v_med3_f32 v168, v168, s47, v225
	v_med3_f32 v169, v169, s47, v225
	v_pk_mul_f32 v[170:171], v[168:169], v[168:169]
	v_and_b32_e32 v161, 0xffff0000, v150
	v_pk_fma_f32 v[172:173], v[170:171], s[34:35], v[148:149] op_sel_hi:[1,0,0] neg_lo:[1,0,0] neg_hi:[1,0,0]
	s_nop 0
	v_pk_fma_f32 v[172:173], v[170:171], v[172:173], s[38:39] op_sel_hi:[1,1,0]
	s_nop 0
	v_pk_fma_f32 v[172:173], v[170:171], v[172:173], s[40:41] op_sel_hi:[1,1,0]
	s_nop 0
	v_pk_fma_f32 v[172:173], v[170:171], v[172:173], s[42:43] op_sel_hi:[1,1,0]
	s_nop 0
	v_pk_fma_f32 v[172:173], v[170:171], v[172:173], s[44:45] op_sel_hi:[1,1,0]
	s_nop 0
	v_pk_fma_f32 v[172:173], v[170:171], v[172:173], s[46:47] op_sel_hi:[1,1,0]
	s_nop 0
	v_pk_fma_f32 v[170:171], v[170:171], v[172:173], s[48:49] op_sel_hi:[1,1,0]
	s_nop 0
	v_pk_mul_f32 v[168:169], v[168:169], v[170:171]
	s_nop 0
	v_pk_fma_f32 v[164:165], v[164:165], v[168:169], v[164:165]
	s_nop 0
	v_mul_f32_e32 v164, v62, v164
	v_mul_f32_e32 v168, v188, v164
	v_mul_f32_e32 v164, v63, v165
	v_mul_f32_e32 v165, v188, v164
	v_cvt_pk_bf16_f32 v164, v174, v175
	v_cvt_pk_bf16_f32 v165, v168, v165
	global_store_dwordx2 v[152:153], v[164:165], off
	v_mov_b32_dpp v153, v227 row_ror:1 row_mask:0xf bank_mask:0xf bound_ctrl:1
	v_mov_b32_dpp v164, v226 row_ror:2 row_mask:0xf bank_mask:0xf bound_ctrl:1
	v_mov_b32_dpp v165, v227 row_ror:2 row_mask:0xf bank_mask:0xf bound_ctrl:1
	v_mov_b32_dpp v153, v227 row_shr:1 row_mask:0xf bank_mask:0xf
	v_mov_b32_dpp v152, v226 row_ror:1 row_mask:0xf bank_mask:0xf bound_ctrl:1
	v_mov_b32_dpp v164, v226 row_shr:2 row_mask:0xf bank_mask:0xf
	v_mov_b32_dpp v165, v227 row_shr:2 row_mask:0xf bank_mask:0xf
	v_and_b32_e32 v170, 0xffff0000, v153
	v_mov_b32_dpp v152, v226 row_shr:1 row_mask:0xf bank_mask:0xf
	v_lshlrev_b32_e32 v172, 16, v164
	v_and_b32_e32 v171, 0xffff0000, v164
	v_lshlrev_b32_e32 v173, 16, v165
	v_and_b32_e32 v174, 0xffff0000, v165
	s_waitcnt vmcnt(1)
	v_cndmask_b32_e64 v165, v170, v215, s[0:1]
	v_cndmask_b32_e32 v170, v178, v212, vcc
	v_cndmask_b32_e32 v175, v179, v213, vcc
	v_lshlrev_b32_e32 v168, 16, v152
	v_and_b32_e32 v152, 0xffff0000, v152
	v_lshlrev_b32_e32 v169, 16, v153
	v_cndmask_b32_e64 v171, v171, v175, s[8:9]
	v_cndmask_b32_e64 v170, v172, v170, s[8:9]
	v_cndmask_b32_e64 v153, v152, v213, s[0:1]
	v_cndmask_b32_e64 v152, v168, v212, s[0:1]
	v_cndmask_b32_e64 v164, v169, v214, s[0:1]
	v_cndmask_b32_e32 v168, v180, v214, vcc
	v_cndmask_b32_e32 v169, v181, v215, vcc
	v_pk_fma_f32 v[170:171], v[140:141], v[170:171], v[144:145]
	v_cndmask_b32_e64 v169, v174, v169, s[8:9]
	v_cndmask_b32_e64 v168, v173, v168, s[8:9]
	v_lshlrev_b32_e32 v172, 16, v226
	v_and_b32_e32 v173, 0xffff0000, v226
	v_pk_fma_f32 v[152:153], v[136:137], v[152:153], v[170:171]
	v_pk_fma_f32 v[168:169], v[142:143], v[168:169], v[146:147]
	v_pk_fma_f32 v[152:153], v[132:133], v[172:173], v[152:153]
	v_pk_fma_f32 v[164:165], v[138:139], v[164:165], v[168:169]
	v_pk_mul_f32 v[168:169], v[152:153], s[30:31] op_sel_hi:[1,0]
	v_pk_mul_f32 v[152:153], v[152:153], 0.5 op_sel_hi:[1,0]
	v_med3_f32 v168, v168, s47, v225
	v_med3_f32 v169, v169, s47, v225
	v_pk_mul_f32 v[170:171], v[168:169], v[168:169]
	v_mov_b32_dpp v178, v162 row_ror:2 row_mask:0xf bank_mask:0xf bound_ctrl:1
	v_pk_fma_f32 v[172:173], v[170:171], s[34:35], v[148:149] op_sel_hi:[1,0,0] neg_lo:[1,0,0] neg_hi:[1,0,0]
	v_mov_b32_dpp v179, v163 row_ror:2 row_mask:0xf bank_mask:0xf bound_ctrl:1
	v_pk_fma_f32 v[172:173], v[170:171], v[172:173], s[38:39] op_sel_hi:[1,1,0]
	v_mov_b32_dpp v178, v162 row_shr:2 row_mask:0xf bank_mask:0xf
	v_pk_fma_f32 v[172:173], v[170:171], v[172:173], s[40:41] op_sel_hi:[1,1,0]
	v_mov_b32_dpp v179, v163 row_shr:2 row_mask:0xf bank_mask:0xf
; __device__ __forceinline__ unsigned cvt_pk_bf16(float lo, float hi) { unsigned r; asm volatile("v_cvt_pk_bf16_f32 %0, %1, %2" : "=v"(r) : "v"(lo), "v"(hi)); return r; }
;     static __device__ __forceinline__ void unpk4(const u32x2 w, float (&o)[4]) { o[0] = bf_lo(w.x); o[1] = bf_hi(w.x); o[2] = bf_lo(w.y); o[3] = bf_hi(w.y); }
;     template <int N> static __device__ __forceinline__ u32x2 dpp_prev(const u32x2 pv, const u32x2 cur) { u32x2 r; r.x = dpp_prev1<N>(pv.x, cur.x); r.y = dpp_prev1<N>(pv.y, cur.y); return r; }
;     static __device__ __forceinline__ void finish(const float (&g0)[4], const float (&g1)[4], const float (&g2)[4], const float (&w0)[4], const float (&w1)[4], const float (&w2)[4], const float (&bb)[4],
;                                                   const f32x4 v, float rs, bf16_t* dst) {
;         float h[4];
; #pragma unroll
;         for (int j = 0; j < 4; j += 2) {
;             const f32x2 gc = (f32x2){bb[j] + w0[j] * g2[j] + w1[j] * g1[j] + w2[j] * g0[j], bb[j + 1] + w0[j + 1] * g2[j + 1] + w1[j + 1] * g1[j + 1] + w2[j + 1] * g0[j + 1]};
;             const f32x2 ge = gelu_pk(gc); h[j] = ge.x * v[j] * rs; h[j + 1] = ge.y * v[j + 1] * rs; }
;         u32x2 w; w.x = cvt_pk_bf16(h[0], h[1]); w.y = cvt_pk_bf16(h[2], h[3]);
;         *(u32x2*)dst = w;
;     }
;     __device__ __forceinline__ void operator()(const f32x4 (&acc)[2][2][4][2], const Unit& u, int wr, int wc, int fr, int fq) const {
;     ...
;                 for (int m = mh; m < mh + 2; ++m) { const int row = row0 + m * 16; const float* cx = ctx + (size_t)((row - 32768) >> 3) * 2 * 2816 + col;
;                     c0[m] = *(const f32x4*)cx; c1[m] = *(const f32x4*)(cx + 2816); }
; #pragma unroll
;                 for (int m = mh; m < mh + 2; ++m) { const int row = row0 + m * 16; const u32x2 cur = gq[m];
;                     const u32x2 q1 = dpp_prev<1>(cur, cur), q2 = dpp_prev<2>(cur, cur);
;                     float g0[4], g1[4], g2[4]; unpk4(cur, g0); unpk4(q1, g1); unpk4(q2, g2);
; #pragma unroll
;                     for (int j = 0; j < 4; ++j) { const float x1 = c1[m][j], x0 = c0[m][j];
;                         if (i < 1) g1[j] = x1;
;                         if (i < 2) g2[j] = (i == 1) ? x1 : x0; }
;                     finish(g0, g1, g2, w0, w1, w2, bb, acc[0][bj][m][hv], rs8[0][m], H + (size_t)row * 2816 + col); }
	v_pk_fma_f32 v[172:173], v[170:171], v[172:173], s[42:43] op_sel_hi:[1,1,0]
	v_lshlrev_b32_e32 v180, 16, v176
	v_pk_fma_f32 v[172:173], v[170:171], v[172:173], s[44:45] op_sel_hi:[1,1,0]
	v_and_b32_e32 v176, 0xffff0000, v176
	v_pk_fma_f32 v[172:173], v[170:171], v[172:173], s[46:47] op_sel_hi:[1,1,0]
	v_lshlrev_b32_e32 v181, 16, v177
	v_pk_fma_f32 v[170:171], v[170:171], v[172:173], s[48:49] op_sel_hi:[1,1,0]
	v_and_b32_e32 v185, 0xffff0000, v178
	v_pk_mul_f32 v[168:169], v[168:169], v[170:171]
	v_lshlrev_b32_e32 v187, 16, v179
	v_pk_fma_f32 v[152:153], v[152:153], v[168:169], v[152:153]
	v_and_b32_e32 v189, 0xffff0000, v179
	v_mul_f32_e32 v152, v52, v152
	v_mul_f32_e32 v172, v186, v152
	v_mul_f32_e32 v152, v53, v153
	v_mul_f32_e32 v173, v186, v152
	v_lshlrev_b32_e32 v152, 16, v227
	v_and_b32_e32 v153, 0xffff0000, v227
	v_pk_fma_f32 v[152:153], v[134:135], v[152:153], v[164:165]
	s_nop 0
	v_pk_mul_f32 v[164:165], v[152:153], s[30:31] op_sel_hi:[1,0]
	v_pk_mul_f32 v[152:153], v[152:153], 0.5 op_sel_hi:[1,0]
	v_med3_f32 v164, v164, s47, v225
	v_med3_f32 v165, v165, s47, v225
	v_pk_mul_f32 v[168:169], v[164:165], v[164:165]
	s_nop 0
	v_pk_fma_f32 v[170:171], v[168:169], s[34:35], v[148:149] op_sel_hi:[1,0,0] neg_lo:[1,0,0] neg_hi:[1,0,0]
	s_nop 0
	v_pk_fma_f32 v[170:171], v[168:169], v[170:171], s[38:39] op_sel_hi:[1,1,0]
	s_nop 0
	v_pk_fma_f32 v[170:171], v[168:169], v[170:171], s[40:41] op_sel_hi:[1,1,0]
	s_nop 0
	v_pk_fma_f32 v[170:171], v[168:169], v[170:171], s[42:43] op_sel_hi:[1,1,0]
	s_nop 0
	v_pk_fma_f32 v[170:171], v[168:169], v[170:171], s[44:45] op_sel_hi:[1,1,0]
	s_nop 0
	v_pk_fma_f32 v[170:171], v[168:169], v[170:171], s[46:47] op_sel_hi:[1,1,0]
	s_nop 0
	v_pk_fma_f32 v[168:169], v[168:169], v[170:171], s[48:49] op_sel_hi:[1,1,0]
	s_nop 0
	v_pk_mul_f32 v[164:165], v[164:165], v[168:169]
	s_nop 0
	v_pk_fma_f32 v[152:153], v[152:153], v[164:165], v[152:153]
	s_nop 0
	v_mul_f32_e32 v152, v54, v152
	v_mul_f32_e32 v164, v186, v152
	v_mul_f32_e32 v152, v55, v153
	v_mul_f32_e32 v153, v186, v152
	v_cvt_pk_bf16_f32 v152, v172, v173
	v_cvt_pk_bf16_f32 v153, v164, v153
	v_mad_i64_i32 v[164:165], s[10:11], v166, s45, v[182:183]
	global_store_dwordx2 v[154:155], v[152:153], off
	v_add_co_u32_e64 v152, s[10:11], s41, v164
	s_nop 1
	v_addc_co_u32_e64 v153, s[10:11], 0, v165, s[10:11]
	global_load_dwordx4 v[152:155], v[152:153], off offset:3072
	s_nop 0
	global_load_dwordx4 v[168:171], v[164:165], off
	v_mad_i64_i32 v[164:165], s[10:11], v167, s45, v[182:183]
	v_add_co_u32_e64 v172, s[10:11], s41, v164
	v_and_b32_e32 v182, 0xffff0000, v177
	s_nop 0
	v_addc_co_u32_e64 v173, s[10:11], 0, v165, s[10:11]
	global_load_dwordx4 v[164:167], v[164:165], off
	s_nop 0
	global_load_dwordx4 v[172:175], v[172:173], off offset:3072
	v_lshlrev_b32_e32 v183, 16, v178
	s_waitcnt vmcnt(3)
	v_cndmask_b32_e64 v177, v176, v153, s[0:1]
	s_waitcnt vmcnt(2)
	v_cndmask_b32_e32 v168, v168, v152, vcc
	v_cndmask_b32_e32 v169, v169, v153, vcc
	v_cndmask_b32_e64 v176, v180, v152, s[0:1]
	v_cndmask_b32_e64 v179, v182, v155, s[0:1]
	v_cndmask_b32_e64 v178, v181, v154, s[0:1]
	v_cndmask_b32_e32 v152, v170, v154, vcc
	v_cndmask_b32_e32 v153, v171, v155, vcc
	v_cndmask_b32_e64 v155, v185, v169, s[8:9]
	v_cndmask_b32_e64 v154, v183, v168, s[8:9]
	v_pk_fma_f32 v[154:155], v[140:141], v[154:155], v[144:145]
	v_lshlrev_b32_e32 v168, 16, v162
	v_and_b32_e32 v169, 0xffff0000, v162
	v_pk_fma_f32 v[154:155], v[136:137], v[176:177], v[154:155]
	v_cndmask_b32_e64 v153, v189, v153, s[8:9]
	v_pk_fma_f32 v[154:155], v[132:133], v[168:169], v[154:155]
	v_cndmask_b32_e64 v152, v187, v152, s[8:9]
	v_pk_mul_f32 v[168:169], v[154:155], s[30:31] op_sel_hi:[1,0]
	v_pk_mul_f32 v[154:155], v[154:155], 0.5 op_sel_hi:[1,0]
	v_med3_f32 v168, v168, s47, v225
	v_med3_f32 v169, v169, s47, v225
	v_pk_mul_f32 v[170:171], v[168:169], v[168:169]
	v_pk_fma_f32 v[152:153], v[142:143], v[152:153], v[146:147]
	v_pk_fma_f32 v[176:177], v[170:171], s[34:35], v[148:149] op_sel_hi:[1,0,0] neg_lo:[1,0,0] neg_hi:[1,0,0]
	v_pk_fma_f32 v[152:153], v[138:139], v[178:179], v[152:153]
	v_pk_fma_f32 v[176:177], v[170:171], v[176:177], s[38:39] op_sel_hi:[1,1,0]
	s_nop 0
	v_pk_fma_f32 v[176:177], v[170:171], v[176:177], s[40:41] op_sel_hi:[1,1,0]
	s_nop 0
	v_pk_fma_f32 v[176:177], v[170:171], v[176:177], s[42:43] op_sel_hi:[1,1,0]
	s_nop 0
	v_pk_fma_f32 v[176:177], v[170:171], v[176:177], s[44:45] op_sel_hi:[1,1,0]
	s_nop 0
	v_pk_fma_f32 v[176:177], v[170:171], v[176:177], s[46:47] op_sel_hi:[1,1,0]
	s_nop 0
	v_pk_fma_f32 v[170:171], v[170:171], v[176:177], s[48:49] op_sel_hi:[1,1,0]
	s_nop 0
	v_pk_mul_f32 v[168:169], v[168:169], v[170:171]
	s_nop 0
	v_pk_fma_f32 v[154:155], v[154:155], v[168:169], v[154:155]
	s_nop 0
	v_mul_f32_e32 v154, v44, v154
	v_mul_f32_e32 v170, v184, v154
	v_mul_f32_e32 v154, v45, v155
	v_mul_f32_e32 v171, v184, v154
	v_lshlrev_b32_e32 v154, 16, v163
	v_and_b32_e32 v155, 0xffff0000, v163
	v_pk_fma_f32 v[152:153], v[134:135], v[154:155], v[152:153]
	s_nop 0
	v_pk_mul_f32 v[154:155], v[152:153], s[30:31] op_sel_hi:[1,0]
	v_pk_mul_f32 v[152:153], v[152:153], 0.5 op_sel_hi:[1,0]
	v_med3_f32 v154, v154, s47, v225
	v_med3_f32 v155, v155, s47, v225
	v_pk_mul_f32 v[162:163], v[154:155], v[154:155]
	s_nop 0
	v_pk_fma_f32 v[168:169], v[162:163], s[34:35], v[148:149] op_sel_hi:[1,0,0] neg_lo:[1,0,0] neg_hi:[1,0,0]
	s_nop 0
	v_pk_fma_f32 v[168:169], v[162:163], v[168:169], s[38:39] op_sel_hi:[1,1,0]
	s_nop 0
	v_pk_fma_f32 v[168:169], v[162:163], v[168:169], s[40:41] op_sel_hi:[1,1,0]
	s_nop 0
	v_pk_fma_f32 v[168:169], v[162:163], v[168:169], s[42:43] op_sel_hi:[1,1,0]
	s_nop 0
	v_pk_fma_f32 v[168:169], v[162:163], v[168:169], s[44:45] op_sel_hi:[1,1,0]
	s_nop 0
	v_pk_fma_f32 v[168:169], v[162:163], v[168:169], s[46:47] op_sel_hi:[1,1,0]
	s_nop 0
	v_pk_fma_f32 v[162:163], v[162:163], v[168:169], s[48:49] op_sel_hi:[1,1,0]
	s_nop 0
	v_pk_mul_f32 v[154:155], v[154:155], v[162:163]
	s_nop 0
	v_pk_fma_f32 v[152:153], v[152:153], v[154:155], v[152:153]
	v_mov_b32_dpp v155, v151 row_ror:2 row_mask:0xf bank_mask:0xf bound_ctrl:1
	v_mul_f32_e32 v152, v46, v152
	v_mul_f32_e32 v154, v184, v152
	v_mul_f32_e32 v152, v47, v153
	v_mul_f32_e32 v153, v184, v152
	v_cvt_pk_bf16_f32 v152, v170, v171
	v_cvt_pk_bf16_f32 v153, v154, v153
	global_store_dwordx2 v[156:157], v[152:153], off
	v_mov_b32_dpp v154, v150 row_ror:2 row_mask:0xf bank_mask:0xf bound_ctrl:1
	v_mov_b32_dpp v153, v151 row_ror:1 row_mask:0xf bank_mask:0xf bound_ctrl:1
	v_mov_b32_dpp v152, v150 row_ror:1 row_mask:0xf bank_mask:0xf bound_ctrl:1
	v_mov_b32_dpp v154, v150 row_shr:2 row_mask:0xf bank_mask:0xf
	v_mov_b32_dpp v153, v151 row_shr:1 row_mask:0xf bank_mask:0xf
	v_mov_b32_dpp v155, v151 row_shr:2 row_mask:0xf bank_mask:0xf
	v_and_b32_e32 v162, 0xffff0000, v153
	v_mov_b32_dpp v152, v150 row_shr:1 row_mask:0xf bank_mask:0xf
	v_lshlrev_b32_e32 v168, 16, v154
	v_and_b32_e32 v163, 0xffff0000, v154
	v_lshlrev_b32_e32 v169, 16, v155
	v_and_b32_e32 v170, 0xffff0000, v155
	s_waitcnt vmcnt(1)
; __device__ __forceinline__ unsigned cvt_pk_bf16(float lo, float hi) { unsigned r; asm volatile("v_cvt_pk_bf16_f32 %0, %1, %2" : "=v"(r) : "v"(lo), "v"(hi)); return r; }
;     static __device__ __forceinline__ void unpk4(const u32x2 w, float (&o)[4]) { o[0] = bf_lo(w.x); o[1] = bf_hi(w.x); o[2] = bf_lo(w.y); o[3] = bf_hi(w.y); }
;     template <int N> static __device__ __forceinline__ u32x2 dpp_prev(const u32x2 pv, const u32x2 cur) { u32x2 r; r.x = dpp_prev1<N>(pv.x, cur.x); r.y = dpp_prev1<N>(pv.y, cur.y); return r; }
;     static __device__ __forceinline__ void finish(const float (&g0)[4], const float (&g1)[4], const float (&g2)[4], const float (&w0)[4], const float (&w1)[4], const float (&w2)[4], const float (&bb)[4],
;                                                   const f32x4 v, float rs, bf16_t* dst) {
;         float h[4];
; #pragma unroll
;         for (int j = 0; j < 4; j += 2) {
;             const f32x2 gc = (f32x2){bb[j] + w0[j] * g2[j] + w1[j] * g1[j] + w2[j] * g0[j], bb[j + 1] + w0[j + 1] * g2[j + 1] + w1[j + 1] * g1[j + 1] + w2[j + 1] * g0[j + 1]};
;             const f32x2 ge = gelu_pk(gc); h[j] = ge.x * v[j] * rs; h[j + 1] = ge.y * v[j + 1] * rs; }
;         u32x2 w; w.x = cvt_pk_bf16(h[0], h[1]); w.y = cvt_pk_bf16(h[2], h[3]);
;         *(u32x2*)dst = w;
;     }
;     __device__ __forceinline__ void operator()(const f32x4 (&acc)[2][2][4][2], const Unit& u, int wr, int wc, int fr, int fq) const {
;     ...
;                 for (int m = mh; m < mh + 2; ++m) { const int row = row0 + m * 16; const u32x2 cur = gq[m];
;                     const u32x2 q1 = dpp_prev<1>(cur, cur), q2 = dpp_prev<2>(cur, cur);
;                     float g0[4], g1[4], g2[4]; unpk4(cur, g0); unpk4(q1, g1); unpk4(q2, g2);
; #pragma unroll
;                     for (int j = 0; j < 4; ++j) { const float x1 = c1[m][j], x0 = c0[m][j];
;                         if (i < 1) g1[j] = x1;
;                         if (i < 2) g2[j] = (i == 1) ? x1 : x0; }
;                     finish(g0, g1, g2, w0, w1, w2, bb, acc[0][bj][m][hv], rs8[0][m], H + (size_t)row * 2816 + col); }
	v_cndmask_b32_e64 v155, v162, v175, s[0:1]
	v_cndmask_b32_e32 v162, v164, v172, vcc
	v_cndmask_b32_e32 v164, v165, v173, vcc
	v_lshlrev_b32_e32 v156, 16, v152
	v_and_b32_e32 v152, 0xffff0000, v152
	v_cndmask_b32_e64 v163, v163, v164, s[8:9]
	v_cndmask_b32_e64 v162, v168, v162, s[8:9]
	v_lshlrev_b32_e32 v157, 16, v153
	v_cndmask_b32_e64 v153, v152, v173, s[0:1]
	v_cndmask_b32_e64 v152, v156, v172, s[0:1]
	v_pk_fma_f32 v[140:141], v[140:141], v[162:163], v[144:145]
	v_cndmask_b32_e64 v154, v157, v174, s[0:1]
	v_pk_fma_f32 v[136:137], v[136:137], v[152:153], v[140:141]
	v_cndmask_b32_e32 v156, v166, v174, vcc
	v_pk_fma_f32 v[132:133], v[132:133], v[160:161], v[136:137]
	v_cndmask_b32_e32 v157, v167, v175, vcc
	v_pk_mul_f32 v[136:137], v[132:133], s[30:31] op_sel_hi:[1,0]
	v_cndmask_b32_e64 v157, v170, v157, s[8:9]
	v_cndmask_b32_e64 v156, v169, v156, s[8:9]
	v_med3_f32 v136, v136, s47, v225
	v_med3_f32 v137, v137, s47, v225
	v_pk_fma_f32 v[142:143], v[142:143], v[156:157], v[146:147]
	v_pk_mul_f32 v[140:141], v[136:137], v[136:137]
	v_pk_fma_f32 v[138:139], v[138:139], v[154:155], v[142:143]
	v_pk_fma_f32 v[142:143], v[140:141], s[34:35], v[148:149] op_sel_hi:[1,0,0] neg_lo:[1,0,0] neg_hi:[1,0,0]
	v_pk_mul_f32 v[132:133], v[132:133], 0.5 op_sel_hi:[1,0]
	v_pk_fma_f32 v[142:143], v[140:141], v[142:143], s[38:39] op_sel_hi:[1,1,0]
	s_mov_b64 s[0:1], 0
	v_pk_fma_f32 v[142:143], v[140:141], v[142:143], s[40:41] op_sel_hi:[1,1,0]
	s_nop 0
	v_pk_fma_f32 v[142:143], v[140:141], v[142:143], s[42:43] op_sel_hi:[1,1,0]
	s_nop 0
	v_pk_fma_f32 v[142:143], v[140:141], v[142:143], s[44:45] op_sel_hi:[1,1,0]
	s_nop 0
	v_pk_fma_f32 v[142:143], v[140:141], v[142:143], s[46:47] op_sel_hi:[1,1,0]
	s_nop 0
	v_pk_fma_f32 v[140:141], v[140:141], v[142:143], s[48:49] op_sel_hi:[1,1,0]
	s_nop 0
	v_pk_mul_f32 v[136:137], v[136:137], v[140:141]
	s_nop 0
	v_pk_fma_f32 v[132:133], v[132:133], v[136:137], v[132:133]
	s_nop 0
	v_mul_f32_e32 v132, v36, v132
	v_mul_f32_e32 v140, v2, v132
	v_mul_f32_e32 v132, v37, v133
	v_mul_f32_e32 v141, v2, v132
	v_lshlrev_b32_e32 v132, 16, v151
	v_and_b32_e32 v133, 0xffff0000, v151
	v_pk_fma_f32 v[132:133], v[134:135], v[132:133], v[138:139]
	s_nop 0
	v_pk_mul_f32 v[134:135], v[132:133], s[30:31] op_sel_hi:[1,0]
	v_pk_mul_f32 v[132:133], v[132:133], 0.5 op_sel_hi:[1,0]
	v_med3_f32 v134, v134, s47, v225
	v_med3_f32 v135, v135, s47, v225
	v_pk_mul_f32 v[136:137], v[134:135], v[134:135]
	s_nop 0
	v_pk_fma_f32 v[138:139], v[136:137], s[34:35], v[148:149] op_sel_hi:[1,0,0] neg_lo:[1,0,0] neg_hi:[1,0,0]
	s_nop 0
	v_pk_fma_f32 v[138:139], v[136:137], v[138:139], s[38:39] op_sel_hi:[1,1,0]
	s_nop 0
	v_pk_fma_f32 v[138:139], v[136:137], v[138:139], s[40:41] op_sel_hi:[1,1,0]
	s_nop 0
	v_pk_fma_f32 v[138:139], v[136:137], v[138:139], s[42:43] op_sel_hi:[1,1,0]
	s_nop 0
	v_pk_fma_f32 v[138:139], v[136:137], v[138:139], s[44:45] op_sel_hi:[1,1,0]
	s_nop 0
	v_pk_fma_f32 v[138:139], v[136:137], v[138:139], s[46:47] op_sel_hi:[1,1,0]
	s_nop 0
	v_pk_fma_f32 v[136:137], v[136:137], v[138:139], s[48:49] op_sel_hi:[1,1,0]
	s_nop 0
	v_pk_mul_f32 v[134:135], v[134:135], v[136:137]
	s_nop 0
	v_pk_fma_f32 v[132:133], v[132:133], v[134:135], v[132:133]
	s_nop 0
	v_mul_f32_e32 v132, v38, v132
	v_mul_f32_e32 v134, v2, v132
	v_mul_f32_e32 v132, v39, v133
	v_mul_f32_e32 v133, v2, v132
	v_cvt_pk_bf16_f32 v132, v140, v141
	v_cvt_pk_bf16_f32 v133, v134, v133
	global_store_dwordx2 v[158:159], v[132:133], off

;     __device__ __forceinline__ void operator()(const f32x4 (&acc)[2][2][4][2], const Unit& u, int wr, int wc, int fr, int fq) const {
;     ...
;         float rs[2][4];
; #pragma unroll
;         for (int ai = 0; ai < 2; ++ai) if (ai == 0 || !u.half)
; #pragma unroll
;             for (int m = 0; m < 4; ++m) rs[ai][m] = rsqrtf(SS[row0 + (u.half ? 0 : ai * HALF) + m * 16] * (1.f / 1024.f) + 1e-6f);
.LBB0_1211:
	v_mov_b32_e32 v128, v157
	v_mov_b32_e32 v130, v159
	s_add_i32 s2, s44, s55
	s_cmp_gt_i32 s45, 3
	v_add_u32_e32 v170, s2, v128
	v_ashrrev_i32_e32 v171, 31, v170
	v_lshl_add_u64 v[128:129], v[170:171], 2, s[10:11]
	global_load_dword v131, v[128:129], off
	global_load_dword v241, v[128:129], off offset:64
	global_load_dword v242, v[128:129], off offset:128
	global_load_dword v243, v[128:129], off offset:192
	global_load_dword v244, v[128:129], off offset:512
	global_load_dword v245, v[128:129], off offset:576
	global_load_dword v246, v[128:129], off offset:640
	global_load_dword v247, v[128:129], off offset:704
	v_lshlrev_b32_e32 v176, 3, v130
	v_lshlrev_b64 v[174:175], 11, v[170:171]
	s_mov_b64 s[44:45], -1
	s_waitcnt vmcnt(0)
	v_fmamk_f32 v131, v131, 0x3a800000, v169
	v_cmp_gt_f32_e32 vcc, s86, v131
	v_mul_f32_e32 v132, 0x4b800000, v131
	s_nop 0
	v_cndmask_b32_e32 v131, v131, v132, vcc
	v_rsq_f32_e32 v131, v131
	s_nop 0
	v_mul_f32_e32 v132, 0x45800000, v131
	v_cndmask_b32_e32 v172, v131, v132, vcc
	v_mov_b32_e32 v131, v241
	v_mov_b32_e32 v173, v172
	v_pk_mul_f32 v[126:127], v[126:127], v[172:173] op_sel_hi:[1,0]
	v_pk_mul_f32 v[124:125], v[124:125], v[172:173] op_sel_hi:[1,0]
	v_pk_mul_f32 v[136:137], v[120:121], v[172:173]
	s_waitcnt vmcnt(0)
	v_fmamk_f32 v131, v131, 0x3a800000, v169
	v_cmp_gt_f32_e32 vcc, s86, v131
	v_mul_f32_e32 v132, 0x4b800000, v131
	s_nop 0
	v_cndmask_b32_e32 v131, v131, v132, vcc
	v_rsq_f32_e32 v131, v131
	s_nop 0
	v_mul_f32_e32 v132, 0x45800000, v131
	v_cndmask_b32_e32 v168, v131, v132, vcc
	v_mov_b32_e32 v131, v242
	s_waitcnt vmcnt(0)
	v_fmamk_f32 v131, v131, 0x3a800000, v169
	v_cmp_gt_f32_e32 vcc, s86, v131
	v_mul_f32_e32 v132, 0x4b800000, v131
	s_nop 0
	v_cndmask_b32_e32 v131, v131, v132, vcc
	v_rsq_f32_e32 v131, v131
	s_nop 0
	v_mul_f32_e32 v132, 0x45800000, v131
	v_cndmask_b32_e32 v166, v131, v132, vcc
	v_mov_b32_e32 v131, v243
	s_waitcnt vmcnt(0)
	v_fmamk_f32 v131, v131, 0x3a800000, v169
	v_cmp_gt_f32_e32 vcc, s86, v131
	v_mul_f32_e32 v132, 0x4b800000, v131
	s_nop 0
	v_cndmask_b32_e32 v131, v131, v132, vcc
	v_rsq_f32_e32 v131, v131
	s_nop 0
	v_mul_f32_e32 v132, 0x45800000, v131
	v_cndmask_b32_e32 v164, v131, v132, vcc
	v_mov_b32_e32 v131, v244
	s_waitcnt vmcnt(0)
	v_fmamk_f32 v131, v131, 0x3a800000, v169
	v_cmp_gt_f32_e32 vcc, s86, v131
	v_mul_f32_e32 v132, 0x4b800000, v131
	s_nop 0
	v_cndmask_b32_e32 v131, v131, v132, vcc
	v_rsq_f32_e32 v131, v131
	s_nop 0
	v_mul_f32_e32 v132, 0x45800000, v131
	v_cndmask_b32_e32 v162, v131, v132, vcc
	v_mov_b32_e32 v131, v245
	s_waitcnt vmcnt(0)
	v_fmamk_f32 v131, v131, 0x3a800000, v169
	v_cmp_gt_f32_e32 vcc, s86, v131
	v_mul_f32_e32 v132, 0x4b800000, v131
	s_nop 0
	v_cndmask_b32_e32 v131, v131, v132, vcc
	v_rsq_f32_e32 v131, v131
	s_nop 0
	v_mul_f32_e32 v132, 0x45800000, v131
	v_cndmask_b32_e32 v160, v131, v132, vcc
	v_mov_b32_e32 v131, v246
	s_waitcnt vmcnt(0)
	v_fmamk_f32 v131, v131, 0x3a800000, v169
	v_mov_b32_e32 v128, v247
	s_nop 0
	s_nop 0
	s_nop 0
	s_nop 0
	s_nop 0
	s_nop 0
	s_nop 0
	s_nop 0
	s_nop 0
	v_cmp_gt_f32_e32 vcc, s86, v131
	v_mul_f32_e32 v132, 0x4b800000, v131
	s_waitcnt vmcnt(0)
	v_fmamk_f32 v128, v128, 0x3a800000, v169
	v_cndmask_b32_e32 v131, v131, v132, vcc
	v_rsq_f32_e32 v131, v131
	v_mul_f32_e32 v129, 0x4b800000, v128
	v_mul_f32_e32 v132, 0x45800000, v131
	v_cndmask_b32_e32 v158, v131, v132, vcc
	v_cmp_gt_f32_e32 vcc, s86, v128
	v_pk_mul_f32 v[132:133], v[116:117], v[172:173]
	s_nop 0
	v_cndmask_b32_e32 v128, v128, v129, vcc
	v_rsq_f32_e32 v128, v128
	s_nop 0
	v_mul_f32_e32 v129, 0x45800000, v128
	v_cndmask_b32_e32 v156, v128, v129, vcc
	v_pk_mul_f32 v[128:129], v[112:113], v[172:173]
	s_cbranch_scc0 .LBB0_1214
;     __device__ __forceinline__ void operator()(const f32x4 (&acc)[2][2][4][2], const Unit& u, int wr, int wc, int fr, int fq) const {
;     ...
;         } else {
;             const int col0 = (u.cb - 1024) + wc * 32 + 8 * fq;
; #pragma unroll
;             for (int ai = 0; ai < 2; ++ai) if (ai == 0 || !u.half)
; #pragma unroll
;                 for (int m = 0; m < 4; ++m) { float* rowp = KV + (size_t)(row0 + ai * HALF + m * 16) * 512 + col0;
; #pragma unroll
;                     for (int bj = 0; bj < 2; ++bj) if (bj == 0 || !u.q) { *(f32x4*)(rowp + bj * HALF) = acc[ai][bj][m][0] * rs[ai][m]; *(f32x4*)(rowp + bj * HALF + 4) = acc[ai][bj][m][1] * rs[ai][m]; } }
	s_add_i32 s2, s71, s1
	v_add_u32_e32 v112, s2, v176
	v_readlane_b32 s2, v240, 58
	v_ashrrev_i32_e32 v113, 31, v112
	v_readlane_b32 s3, v240, 59
	v_lshlrev_b64 v[112:113], 2, v[112:113]
	v_pk_mul_f32 v[180:181], v[110:111], v[168:169] op_sel_hi:[1,0]
	v_lshl_add_u64 v[116:117], s[2:3], 0, v[174:175]
	v_lshl_add_u64 v[112:113], v[116:117], 0, v[112:113]
	v_add_co_u32_e32 v120, vcc, s73, v112
	s_mov_b64 s[2:3], 0x8000
	v_pk_mul_f32 v[178:179], v[108:109], v[168:169] op_sel_hi:[1,0]
	v_addc_co_u32_e32 v121, vcc, 0, v113, vcc
	v_lshl_add_u64 v[116:117], v[112:113], 0, s[2:3]
	global_store_dwordx4 v[120:121], v[178:181], off
	v_add_co_u32_e32 v120, vcc, s59, v112
	s_nop 0
	v_pk_mul_f32 v[180:181], v[106:107], v[168:169] op_sel_hi:[1,0]
	v_pk_mul_f32 v[178:179], v[104:105], v[168:169] op_sel_hi:[1,0]
	global_store_dwordx4 v[116:117], v[178:181], off offset:16
	v_addc_co_u32_e32 v121, vcc, 0, v113, vcc
	s_nop 0
	v_pk_mul_f32 v[180:181], v[102:103], v[168:169] op_sel_hi:[1,0]
	v_pk_mul_f32 v[178:179], v[100:101], v[168:169] op_sel_hi:[1,0]
	global_store_dwordx4 v[116:117], v[178:181], off offset:512
	v_mov_b32_e32 v173, v172
	v_pk_mul_f32 v[138:139], v[122:123], v[172:173]
	v_pk_mul_f32 v[180:181], v[94:95], v[168:169] op_sel_hi:[1,0]
	v_pk_mul_f32 v[178:179], v[92:93], v[168:169] op_sel_hi:[1,0]
	global_store_dwordx4 v[116:117], v[178:181], off offset:528
	v_lshl_add_u64 v[116:117], v[112:113], 0, s[18:19]
	v_pk_mul_f32 v[134:135], v[118:119], v[172:173]
	v_pk_mul_f32 v[180:181], v[98:99], v[166:167] op_sel_hi:[1,0]
	v_pk_mul_f32 v[178:179], v[96:97], v[166:167] op_sel_hi:[1,0]
	global_store_dwordx4 v[120:121], v[178:181], off
	v_add_co_u32_e32 v120, vcc, s72, v112
	s_nop 0
	v_pk_mul_f32 v[180:181], v[90:91], v[166:167] op_sel_hi:[1,0]
	v_pk_mul_f32 v[178:179], v[88:89], v[166:167] op_sel_hi:[1,0]
	global_store_dwordx4 v[116:117], v[178:181], off offset:16
	v_addc_co_u32_e32 v121, vcc, 0, v113, vcc
	s_nop 0
	v_pk_mul_f32 v[180:181], v[86:87], v[166:167] op_sel_hi:[1,0]
	v_pk_mul_f32 v[178:179], v[84:85], v[166:167] op_sel_hi:[1,0]
	global_store_dwordx4 v[116:117], v[178:181], off offset:512
	v_pk_mul_f32 v[130:131], v[114:115], v[172:173]
	global_store_dwordx4 v[112:113], v[124:127], off
	v_pk_mul_f32 v[180:181], v[78:79], v[166:167] op_sel_hi:[1,0]
	v_pk_mul_f32 v[178:179], v[76:77], v[166:167] op_sel_hi:[1,0]
	global_store_dwordx4 v[116:117], v[178:181], off offset:528
	v_lshl_add_u64 v[116:117], v[112:113], 0, s[20:21]
	global_store_dwordx4 v[112:113], v[136:139], off offset:16
	v_pk_mul_f32 v[180:181], v[82:83], v[164:165] op_sel_hi:[1,0]
	v_pk_mul_f32 v[178:179], v[80:81], v[164:165] op_sel_hi:[1,0]
	global_store_dwordx4 v[120:121], v[178:181], off
	v_add_co_u32_e32 v120, vcc, s87, v112
	s_nop 0
	v_pk_mul_f32 v[180:181], v[74:75], v[164:165] op_sel_hi:[1,0]
	v_pk_mul_f32 v[178:179], v[72:73], v[164:165] op_sel_hi:[1,0]
	global_store_dwordx4 v[116:117], v[178:181], off offset:16
	v_addc_co_u32_e32 v121, vcc, 0, v113, vcc
	s_nop 0
	v_pk_mul_f32 v[180:181], v[70:71], v[164:165] op_sel_hi:[1,0]
	v_pk_mul_f32 v[178:179], v[68:69], v[164:165] op_sel_hi:[1,0]
	global_store_dwordx4 v[116:117], v[178:181], off offset:512
	global_store_dwordx4 v[112:113], v[132:135], off offset:512
	global_store_dwordx4 v[112:113], v[128:131], off offset:528
	v_pk_mul_f32 v[180:181], v[66:67], v[164:165] op_sel_hi:[1,0]
	v_pk_mul_f32 v[178:179], v[64:65], v[164:165] op_sel_hi:[1,0]
	global_store_dwordx4 v[116:117], v[178:181], off offset:528
	v_lshl_add_u64 v[116:117], v[112:113], 0, s[60:61]
	s_nop 0
	v_pk_mul_f32 v[180:181], v[62:63], v[162:163] op_sel_hi:[1,0]
	v_pk_mul_f32 v[178:179], v[60:61], v[162:163] op_sel_hi:[1,0]
	global_store_dwordx4 v[120:121], v[178:181], off
	v_add_co_u32_e32 v120, vcc, s91, v112
	s_nop 0
	v_pk_mul_f32 v[180:181], v[58:59], v[162:163] op_sel_hi:[1,0]
	v_pk_mul_f32 v[178:179], v[56:57], v[162:163] op_sel_hi:[1,0]
	global_store_dwordx4 v[116:117], v[178:181], off offset:16
	v_addc_co_u32_e32 v121, vcc, 0, v113, vcc
	s_nop 0
	v_pk_mul_f32 v[180:181], v[54:55], v[162:163] op_sel_hi:[1,0]
	v_pk_mul_f32 v[178:179], v[52:53], v[162:163] op_sel_hi:[1,0]
	global_store_dwordx4 v[116:117], v[178:181], off offset:512
	s_nop 1
	v_pk_mul_f32 v[180:181], v[46:47], v[162:163] op_sel_hi:[1,0]
	v_pk_mul_f32 v[178:179], v[44:45], v[162:163] op_sel_hi:[1,0]
	global_store_dwordx4 v[116:117], v[178:181], off offset:528
	v_lshl_add_u64 v[116:117], v[112:113], 0, s[28:29]
	s_nop 0
	v_pk_mul_f32 v[180:181], v[50:51], v[160:161] op_sel_hi:[1,0]
	v_pk_mul_f32 v[178:179], v[48:49], v[160:161] op_sel_hi:[1,0]
	global_store_dwordx4 v[120:121], v[178:181], off
	v_add_co_u32_e32 v120, vcc, s5, v112
	s_nop 0
	v_pk_mul_f32 v[180:181], v[42:43], v[160:161] op_sel_hi:[1,0]
	v_pk_mul_f32 v[178:179], v[40:41], v[160:161] op_sel_hi:[1,0]
	global_store_dwordx4 v[116:117], v[178:181], off offset:16
	v_addc_co_u32_e32 v121, vcc, 0, v113, vcc
	s_nop 0
	v_pk_mul_f32 v[180:181], v[38:39], v[160:161] op_sel_hi:[1,0]
	v_pk_mul_f32 v[178:179], v[36:37], v[160:161] op_sel_hi:[1,0]
	global_store_dwordx4 v[116:117], v[178:181], off offset:512
	s_nop 1
	v_pk_mul_f32 v[180:181], v[30:31], v[160:161] op_sel_hi:[1,0]
	v_pk_mul_f32 v[178:179], v[28:29], v[160:161] op_sel_hi:[1,0]
	global_store_dwordx4 v[116:117], v[178:181], off offset:528
	v_lshl_add_u64 v[116:117], v[112:113], 0, s[30:31]
	s_nop 0
	v_pk_mul_f32 v[180:181], v[34:35], v[158:159] op_sel_hi:[1,0]
	v_pk_mul_f32 v[178:179], v[32:33], v[158:159] op_sel_hi:[1,0]
	global_store_dwordx4 v[120:121], v[178:181], off
	s_nop 1
	v_pk_mul_f32 v[180:181], v[26:27], v[158:159] op_sel_hi:[1,0]
	v_pk_mul_f32 v[178:179], v[24:25], v[158:159] op_sel_hi:[1,0]
	global_store_dwordx4 v[116:117], v[178:181], off offset:16
	s_nop 1
	v_pk_mul_f32 v[180:181], v[22:23], v[158:159] op_sel_hi:[1,0]
	v_pk_mul_f32 v[178:179], v[20:21], v[158:159] op_sel_hi:[1,0]
	global_store_dwordx4 v[116:117], v[178:181], off offset:512
	s_nop 1
	v_pk_mul_f32 v[180:181], v[14:15], v[158:159] op_sel_hi:[1,0]
	v_pk_mul_f32 v[178:179], v[12:13], v[158:159] op_sel_hi:[1,0]
	global_store_dwordx4 v[116:117], v[178:181], off offset:528
	v_lshl_add_u64 v[116:117], v[112:113], 0, s[34:35]
	v_add_co_u32_e32 v112, vcc, s54, v112
	v_pk_mul_f32 v[180:181], v[18:19], v[156:157] op_sel_hi:[1,0]
	v_pk_mul_f32 v[178:179], v[16:17], v[156:157] op_sel_hi:[1,0]
	v_addc_co_u32_e32 v113, vcc, 0, v113, vcc
	global_store_dwordx4 v[112:113], v[178:181], off
	s_nop 1
	v_pk_mul_f32 v[180:181], v[10:11], v[156:157] op_sel_hi:[1,0]
	v_pk_mul_f32 v[178:179], v[8:9], v[156:157] op_sel_hi:[1,0]
	global_store_dwordx4 v[116:117], v[178:181], off offset:16
	s_nop 1
	v_pk_mul_f32 v[180:181], v[6:7], v[156:157] op_sel_hi:[1,0]
	v_pk_mul_f32 v[178:179], v[4:5], v[156:157] op_sel_hi:[1,0]
	global_store_dwordx4 v[116:117], v[178:181], off offset:512
	s_nop 1
	v_pk_mul_f32 v[180:181], v[2:3], v[156:157] op_sel_hi:[1,0]
	v_pk_mul_f32 v[178:179], v[0:1], v[156:157] op_sel_hi:[1,0]
	global_store_dwordx4 v[116:117], v[178:181], off offset:528
	s_cbranch_execz .LBB0_1215

; __device__ __forceinline__ unsigned xb_ld(unsigned* p)              { return __hip_atomic_load(p, __ATOMIC_RELAXED, __HIP_MEMORY_SCOPE_AGENT); }
; __device__ __forceinline__ unsigned xb_add(unsigned* p, unsigned v) { return __hip_atomic_fetch_add(p, v, __ATOMIC_RELAXED, __HIP_MEMORY_SCOPE_AGENT); }
; #define XB_SPIN(cond, bar) do { unsigned _sp = 0; while (cond) { __builtin_amdgcn_s_sleep(1); \
;     if ((++_sp & 255u) == 0u) { if (xb_ld(&(bar)[XB_TMO])) break; if (_sp > XB_SPIN_CAP) { atomicAdd(&(bar)[XB_TMO], 1u); break; } } } } while (0)
; #define GSYNC() do { for (int r_ = 0; r_ < REP_SYNC; ++r_) xcd_barrier(xbar); } while (0)
; __device__ __forceinline__ void xcd_barrier(const XcdBarrier& b) {
;     asm volatile("s_waitcnt vmcnt(0)" ::: "memory");
;     __syncthreads();
;     if (threadIdx.x == 0) {
;         unsigned* bar = b.bar;
;         __builtin_amdgcn_s_waitcnt(0);
;         unsigned nloc = b.st[0], nx = b.st[1];
;         if (nloc == 0u) { xcd_barrier_complete(bar, b.x, nloc, nx); b.st[0] = nloc; b.st[1] = nx; }
;         const unsigned old = xb_add(&bar[XB_XSUB(b.x)], 1u);
;         const unsigned gen = old / nloc;
;         if (old + 1u == (gen + 1u) * nloc) {
;             __builtin_amdgcn_fence(__ATOMIC_RELEASE, "agent");
;             asm volatile("s_waitcnt vmcnt(0)" ::: "memory");
;             const unsigned og = xb_add(&bar[XB_TOP], 1u);
;             const unsigned tg = og / nx;
;             if (og + 1u == (tg + 1u) * nx) xb_add(&bar[XB_TOPGEN], 1u);
;             else XB_SPIN(xb_ld(&bar[XB_TOPGEN]) == tg, bar);
;             __builtin_amdgcn_fence(__ATOMIC_ACQUIRE, "agent");
;             xb_add(&bar[XB_XGEN(b.x)], 1u);
;             asm volatile("s_waitcnt vmcnt(0)" ::: "memory");
;         } else {
;             XB_SPIN(xb_ld(&bar[XB_XGEN(b.x)]) == gen, bar);
;             __builtin_amdgcn_fence(__ATOMIC_ACQUIRE, "agent");
;             asm volatile("s_waitcnt vmcnt(0)" ::: "memory");
;         }
;     }
;     __syncthreads();
; }
; __global__ void __launch_bounds__(NTHR, 2) fwd_megakernel(Params p) {
;     ...
;         GSYNC();
.LBB0_3254:
	s_endpgm

; __global__ void __launch_bounds__(NTHR, 2) fwd_megakernel(Params p) {
	.amdhsa_kernel _Z14fwd_megakernel6Params
		.amdhsa_group_segment_fixed_size 0
		.amdhsa_private_segment_fixed_size 0
		.amdhsa_kernarg_size 544
		.amdhsa_user_sgpr_count 2
		.amdhsa_user_sgpr_dispatch_ptr 0
		.amdhsa_user_sgpr_queue_ptr 0
		.amdhsa_user_sgpr_kernarg_segment_ptr 1
		.amdhsa_user_sgpr_dispatch_id 0
		.amdhsa_user_sgpr_kernarg_preload_length 0
		.amdhsa_user_sgpr_kernarg_preload_offset 0
		.amdhsa_user_sgpr_private_segment_size 0
		.amdhsa_uses_dynamic_stack 0
		.amdhsa_enable_private_segment 0
		.amdhsa_system_sgpr_workgroup_id_x 1
		.amdhsa_system_sgpr_workgroup_id_y 0
		.amdhsa_system_sgpr_workgroup_id_z 0
		.amdhsa_system_sgpr_workgroup_info 0
		.amdhsa_system_vgpr_workitem_id 2
		.amdhsa_next_free_vgpr 249
		.amdhsa_next_free_sgpr 102
		.amdhsa_accum_offset 252
		.amdhsa_reserve_vcc 1
		.amdhsa_float_round_mode_32 0
		.amdhsa_float_round_mode_16_64 0
		.amdhsa_float_denorm_mode_32 3
		.amdhsa_float_denorm_mode_16_64 3
		.amdhsa_dx10_clamp 1
		.amdhsa_ieee_mode 1
		.amdhsa_fp16_overflow 0
		.amdhsa_tg_split 0
		.amdhsa_exception_fp_ieee_invalid_op 0
		.amdhsa_exception_fp_denorm_src 0
		.amdhsa_exception_fp_ieee_div_zero 0
		.amdhsa_exception_fp_ieee_overflow 0
		.amdhsa_exception_fp_ieee_underflow 0
		.amdhsa_exception_fp_ieee_inexact 0
		.amdhsa_exception_int_div_zero 0
	.end_amdhsa_kernel

; __global__ void __launch_bounds__(NTHR, 2) fwd_megakernel(Params p) {
amdhsa.kernels:
  - .agpr_count:     0
    .args:
      - .offset:         0
        .size:           288
        .value_kind:     by_value
      - .offset:         288
        .size:           4
        .value_kind:     hidden_block_count_x
      - .offset:         292
        .size:           4
        .value_kind:     hidden_block_count_y
      - .offset:         296
        .size:           4
        .value_kind:     hidden_block_count_z
      - .offset:         300
        .size:           2
        .value_kind:     hidden_group_size_x
      - .offset:         302
        .size:           2
        .value_kind:     hidden_group_size_y
      - .offset:         304
        .size:           2
        .value_kind:     hidden_group_size_z
      - .offset:         306
        .size:           2
        .value_kind:     hidden_remainder_x
      - .offset:         308
        .size:           2
        .value_kind:     hidden_remainder_y
      - .offset:         310
        .size:           2
        .value_kind:     hidden_remainder_z
      - .offset:         328
        .size:           8
        .value_kind:     hidden_global_offset_x
      - .offset:         336
        .size:           8
        .value_kind:     hidden_global_offset_y
      - .offset:         344
        .size:           8
        .value_kind:     hidden_global_offset_z
      - .offset:         352
        .size:           2
        .value_kind:     hidden_grid_dims
      - .offset:         376
        .size:           8
        .value_kind:     hidden_multigrid_sync_arg
      - .offset:         408
        .size:           4
        .value_kind:     hidden_dynamic_lds_size
    .group_segment_fixed_size: 0
    .kernarg_segment_align: 8
    .kernarg_segment_size: 544
    .language:       OpenCL C
    .language_version:
      - 2
      - 0
    .max_flat_workgroup_size: 512
    .name:           _Z14fwd_megakernel6Params
    .private_segment_fixed_size: 0
    .sgpr_count:     108
    .sgpr_spill_count: 199
    .symbol:         _Z14fwd_megakernel6Params.kd
    .uniform_work_group_size: 1
    .uses_dynamic_stack: false
    .vgpr_count:     249
    .vgpr_spill_count: 0
    .wavefront_size: 64
